# in-proj K-loop: LDS-DMA loads use SGPR base + 32-bit lane offset (no VALU address adds) on top of v063
# speedup vs baseline: 1.0060x; 1.0060x over previous
.LBB0_241:
	s_add_u32 s0, s42, 0xfff00080
	s_addc_u32 s44, s43, -1
	s_add_i32 s67, 0, 0x10000
	v_add_u32_e32 v142, s67, v145
	ds_read_b128 v[148:151], v142
	ds_read_b128 v[152:155], v142 offset:1024
	ds_read_b128 v[156:159], v142 offset:2048
	ds_read_b128 v[160:163], v142 offset:3072
	v_add_u32_e32 v142, s14, v145
	ds_read_b128 v[164:167], v142
	ds_read_b128 v[168:171], v142 offset:1024
	ds_read_b128 v[172:175], v142 offset:2048
	ds_read_b128 v[176:179], v142 offset:3072
	s_cmp_eq_u32 s66, 60
	s_cselect_b32 s47, s11, s44
	s_cselect_b32 s46, s62, s0
	s_cselect_b32 s45, s9, s65
	s_cselect_b32 s44, s63, s64
	s_add_i32 m0, s51, 0xc000
	ds_read_b128 v[180:183], v147
	ds_read_b128 v[184:187], v147 offset:1024
	ds_read_b128 v[188:191], v147 offset:2048
	ds_read_b128 v[218:221], v147 offset:3072
	ds_read_b128 v[222:225], v147 offset:4096
	ds_read_b128 v[226:229], v147 offset:5120
	ds_read_b128 v[230:233], v147 offset:6144
	ds_read_b128 v[234:237], v147 offset:7168
	global_load_lds_dwordx4 v138, s[42:43]
	s_add_i32 m0, s51, 0xe000
	s_nop 0
	global_load_lds_dwordx4 v140, s[42:43]
	s_waitcnt vmcnt(8)
	s_waitcnt lgkmcnt(0)
	s_barrier
	s_setprio 1
	s_waitcnt lgkmcnt(0)
	v_mfma_f32_16x16x32_bf16 v[126:129], v[148:151], v[180:183], v[126:129]
	v_mfma_f32_16x16x32_bf16 v[122:125], v[156:159], v[180:183], v[122:125]
	v_mfma_f32_16x16x32_bf16 v[118:121], v[148:151], v[188:191], v[118:121]
	v_mfma_f32_16x16x32_bf16 v[110:113], v[156:159], v[188:191], v[110:113]
	v_mfma_f32_16x16x32_bf16 v[102:105], v[148:151], v[222:225], v[102:105]
	v_mfma_f32_16x16x32_bf16 v[94:97], v[156:159], v[222:225], v[94:97]
	v_mfma_f32_16x16x32_bf16 v[86:89], v[148:151], v[230:233], v[86:89]
	v_mfma_f32_16x16x32_bf16 v[78:81], v[156:159], v[230:233], v[78:81]
	v_mfma_f32_16x16x32_bf16 v[126:129], v[152:155], v[184:187], v[126:129]
	v_mfma_f32_16x16x32_bf16 v[122:125], v[160:163], v[184:187], v[122:125]
	v_mfma_f32_16x16x32_bf16 v[118:121], v[152:155], v[218:221], v[118:121]
	v_mfma_f32_16x16x32_bf16 v[110:113], v[160:163], v[218:221], v[110:113]
	v_mfma_f32_16x16x32_bf16 v[102:105], v[152:155], v[226:229], v[102:105]
	v_mfma_f32_16x16x32_bf16 v[94:97], v[160:163], v[226:229], v[94:97]
	v_mfma_f32_16x16x32_bf16 v[86:89], v[152:155], v[234:237], v[86:89]
	v_mfma_f32_16x16x32_bf16 v[78:81], v[160:163], v[234:237], v[78:81]
	s_setprio 0
	s_setprio 1
	v_mfma_f32_16x16x32_bf16 v[114:117], v[164:167], v[180:183], v[114:117]
	v_mfma_f32_16x16x32_bf16 v[106:109], v[172:175], v[180:183], v[106:109]
	v_mfma_f32_16x16x32_bf16 v[98:101], v[164:167], v[188:191], v[98:101]
	v_mfma_f32_16x16x32_bf16 v[90:93], v[172:175], v[188:191], v[90:93]
	v_mfma_f32_16x16x32_bf16 v[82:85], v[164:167], v[222:225], v[82:85]
	v_mfma_f32_16x16x32_bf16 v[74:77], v[172:175], v[222:225], v[74:77]
	v_mfma_f32_16x16x32_bf16 v[70:73], v[164:167], v[230:233], v[70:73]
	v_mfma_f32_16x16x32_bf16 v[66:69], v[172:175], v[230:233], v[66:69]
	v_mfma_f32_16x16x32_bf16 v[114:117], v[168:171], v[184:187], v[114:117]
	v_mfma_f32_16x16x32_bf16 v[106:109], v[176:179], v[184:187], v[106:109]
	v_mfma_f32_16x16x32_bf16 v[98:101], v[168:171], v[218:221], v[98:101]
	v_mfma_f32_16x16x32_bf16 v[90:93], v[176:179], v[218:221], v[90:93]
	v_mfma_f32_16x16x32_bf16 v[82:85], v[168:171], v[226:229], v[82:85]
	v_mfma_f32_16x16x32_bf16 v[74:77], v[176:179], v[226:229], v[74:77]
	v_mfma_f32_16x16x32_bf16 v[70:73], v[168:171], v[234:237], v[70:73]
	v_mfma_f32_16x16x32_bf16 v[66:69], v[176:179], v[234:237], v[66:69]
	s_setprio 0
	s_barrier
	s_add_i32 s0, s67, s50
	s_mov_b32 m0, s0
	ds_read_b128 v[180:183], v147 offset:16384
	ds_read_b128 v[184:187], v147 offset:17408
	ds_read_b128 v[188:191], v147 offset:18432
	ds_read_b128 v[218:221], v147 offset:19456
	ds_read_b128 v[222:225], v147 offset:20480
	ds_read_b128 v[226:229], v147 offset:21504
	ds_read_b128 v[230:233], v147 offset:22528
	ds_read_b128 v[234:237], v147 offset:23552
	global_load_lds_dwordx4 v134, s[44:45]
	s_add_i32 m0, s0, 0x2000
	s_add_u32 s68, s44, 0x100000
	s_addc_u32 s69, s45, 0
	s_add_i32 s0, s14, s50
	global_load_lds_dwordx4 v130, s[44:45]
	s_mov_b32 m0, s0
	s_nop 0
	global_load_lds_dwordx4 v134, s[68:69]
	s_add_i32 m0, s0, 0x2000
	s_nop 0
	global_load_lds_dwordx4 v130, s[68:69]
	s_mov_b32 m0, s51
	s_nop 0
	global_load_lds_dwordx4 v136, s[46:47]
	s_mov_b32 m0, s52
	s_nop 0
	global_load_lds_dwordx4 v132, s[46:47]
	s_waitcnt vmcnt(8)
	s_waitcnt lgkmcnt(0)
	s_barrier
	s_setprio 1
	s_waitcnt lgkmcnt(0)
	v_mfma_f32_16x16x32_bf16 v[62:65], v[148:151], v[180:183], v[62:65]
	v_mfma_f32_16x16x32_bf16 v[58:61], v[156:159], v[180:183], v[58:61]
	v_mfma_f32_16x16x32_bf16 v[54:57], v[148:151], v[188:191], v[54:57]
	v_mfma_f32_16x16x32_bf16 v[46:49], v[156:159], v[188:191], v[46:49]
	v_mfma_f32_16x16x32_bf16 v[38:41], v[148:151], v[222:225], v[38:41]
	v_mfma_f32_16x16x32_bf16 v[30:33], v[156:159], v[222:225], v[30:33]
	v_mfma_f32_16x16x32_bf16 v[22:25], v[148:151], v[230:233], v[22:25]
	v_mfma_f32_16x16x32_bf16 v[14:17], v[156:159], v[230:233], v[14:17]
	v_mfma_f32_16x16x32_bf16 v[62:65], v[152:155], v[184:187], v[62:65]
	v_mfma_f32_16x16x32_bf16 v[58:61], v[160:163], v[184:187], v[58:61]
	v_mfma_f32_16x16x32_bf16 v[54:57], v[152:155], v[218:221], v[54:57]
	v_mfma_f32_16x16x32_bf16 v[46:49], v[160:163], v[218:221], v[46:49]
	v_mfma_f32_16x16x32_bf16 v[38:41], v[152:155], v[226:229], v[38:41]
	v_mfma_f32_16x16x32_bf16 v[30:33], v[160:163], v[226:229], v[30:33]
	v_mfma_f32_16x16x32_bf16 v[22:25], v[152:155], v[234:237], v[22:25]
	v_mfma_f32_16x16x32_bf16 v[14:17], v[160:163], v[234:237], v[14:17]
	s_setprio 0
	s_setprio 1
	v_mfma_f32_16x16x32_bf16 v[50:53], v[164:167], v[180:183], v[50:53]
	v_mfma_f32_16x16x32_bf16 v[42:45], v[172:175], v[180:183], v[42:45]
	v_mfma_f32_16x16x32_bf16 v[34:37], v[164:167], v[188:191], v[34:37]
	v_mfma_f32_16x16x32_bf16 v[26:29], v[172:175], v[188:191], v[26:29]
	v_mfma_f32_16x16x32_bf16 v[18:21], v[164:167], v[222:225], v[18:21]
	v_mfma_f32_16x16x32_bf16 v[10:13], v[172:175], v[222:225], v[10:13]
	v_mfma_f32_16x16x32_bf16 v[6:9], v[164:167], v[230:233], v[6:9]
	v_mfma_f32_16x16x32_bf16 v[2:5], v[172:175], v[230:233], v[2:5]
	v_mfma_f32_16x16x32_bf16 v[50:53], v[168:171], v[184:187], v[50:53]
	v_mfma_f32_16x16x32_bf16 v[42:45], v[176:179], v[184:187], v[42:45]
	v_mfma_f32_16x16x32_bf16 v[34:37], v[168:171], v[218:221], v[34:37]
	v_mfma_f32_16x16x32_bf16 v[26:29], v[176:179], v[218:221], v[26:29]
	v_mfma_f32_16x16x32_bf16 v[18:21], v[168:171], v[226:229], v[18:21]
	v_mfma_f32_16x16x32_bf16 v[10:13], v[176:179], v[226:229], v[10:13]
	v_mfma_f32_16x16x32_bf16 v[6:9], v[168:171], v[234:237], v[6:9]
	v_mfma_f32_16x16x32_bf16 v[2:5], v[176:179], v[234:237], v[2:5]
	s_setprio 0
	s_barrier
	s_add_i32 s0, 0, 0x18000
	s_add_i32 s67, 0, 0x1c000
	v_add_u32_e32 v160, s0, v145
	v_add_u32_e32 v176, s67, v145
	ds_read_b128 v[148:151], v160
	ds_read_b128 v[152:155], v160 offset:1024
	ds_read_b128 v[156:159], v160 offset:2048
	ds_read_b128 v[160:163], v160 offset:3072
	ds_read_b128 v[164:167], v176
	ds_read_b128 v[168:171], v176 offset:1024
	ds_read_b128 v[172:175], v176 offset:2048
	ds_read_b128 v[176:179], v176 offset:3072
	s_add_u32 s46, s46, 0x100000
	s_addc_u32 s47, s47, 0
	s_mov_b32 m0, s53
	ds_read_b128 v[180:183], v147 offset:32768
	ds_read_b128 v[184:187], v147 offset:33792
	ds_read_b128 v[188:191], v147 offset:34816
	ds_read_b128 v[218:221], v147 offset:35840
	ds_read_b128 v[222:225], v147 offset:36864
	ds_read_b128 v[226:229], v147 offset:37888
	ds_read_b128 v[230:233], v147 offset:38912
	ds_read_b128 v[234:237], v147 offset:39936
	global_load_lds_dwordx4 v136, s[46:47]
	s_mov_b32 m0, s54
	s_nop 0
	global_load_lds_dwordx4 v132, s[46:47]
	s_waitcnt vmcnt(8)
	s_waitcnt lgkmcnt(0)
	s_barrier
	s_setprio 1
	s_waitcnt lgkmcnt(0)
	v_mfma_f32_16x16x32_bf16 v[126:129], v[148:151], v[180:183], v[126:129]
	v_mfma_f32_16x16x32_bf16 v[122:125], v[156:159], v[180:183], v[122:125]
	v_mfma_f32_16x16x32_bf16 v[118:121], v[148:151], v[188:191], v[118:121]
	v_mfma_f32_16x16x32_bf16 v[110:113], v[156:159], v[188:191], v[110:113]
	v_mfma_f32_16x16x32_bf16 v[102:105], v[148:151], v[222:225], v[102:105]
	v_mfma_f32_16x16x32_bf16 v[94:97], v[156:159], v[222:225], v[94:97]
	v_mfma_f32_16x16x32_bf16 v[86:89], v[148:151], v[230:233], v[86:89]
	v_mfma_f32_16x16x32_bf16 v[78:81], v[156:159], v[230:233], v[78:81]
	v_mfma_f32_16x16x32_bf16 v[126:129], v[152:155], v[184:187], v[126:129]
	v_mfma_f32_16x16x32_bf16 v[122:125], v[160:163], v[184:187], v[122:125]
	v_mfma_f32_16x16x32_bf16 v[118:121], v[152:155], v[218:221], v[118:121]
	v_mfma_f32_16x16x32_bf16 v[110:113], v[160:163], v[218:221], v[110:113]
	v_mfma_f32_16x16x32_bf16 v[102:105], v[152:155], v[226:229], v[102:105]
	v_mfma_f32_16x16x32_bf16 v[94:97], v[160:163], v[226:229], v[94:97]
	v_mfma_f32_16x16x32_bf16 v[86:89], v[152:155], v[234:237], v[86:89]
	v_mfma_f32_16x16x32_bf16 v[78:81], v[160:163], v[234:237], v[78:81]
	s_setprio 0
	s_setprio 1
	v_mfma_f32_16x16x32_bf16 v[114:117], v[164:167], v[180:183], v[114:117]
	v_mfma_f32_16x16x32_bf16 v[106:109], v[172:175], v[180:183], v[106:109]
	v_mfma_f32_16x16x32_bf16 v[98:101], v[164:167], v[188:191], v[98:101]
	v_mfma_f32_16x16x32_bf16 v[90:93], v[172:175], v[188:191], v[90:93]
	v_mfma_f32_16x16x32_bf16 v[82:85], v[164:167], v[222:225], v[82:85]
	v_mfma_f32_16x16x32_bf16 v[74:77], v[172:175], v[222:225], v[74:77]
	v_mfma_f32_16x16x32_bf16 v[70:73], v[164:167], v[230:233], v[70:73]
	v_mfma_f32_16x16x32_bf16 v[66:69], v[172:175], v[230:233], v[66:69]
	v_mfma_f32_16x16x32_bf16 v[114:117], v[168:171], v[184:187], v[114:117]
	v_mfma_f32_16x16x32_bf16 v[106:109], v[176:179], v[184:187], v[106:109]
	v_mfma_f32_16x16x32_bf16 v[98:101], v[168:171], v[218:221], v[98:101]
	v_mfma_f32_16x16x32_bf16 v[90:93], v[176:179], v[218:221], v[90:93]
	v_mfma_f32_16x16x32_bf16 v[82:85], v[168:171], v[226:229], v[82:85]
	v_mfma_f32_16x16x32_bf16 v[74:77], v[176:179], v[226:229], v[74:77]
	v_mfma_f32_16x16x32_bf16 v[70:73], v[168:171], v[234:237], v[70:73]
	v_mfma_f32_16x16x32_bf16 v[66:69], v[176:179], v[234:237], v[66:69]
	s_setprio 0
	s_barrier
	s_add_i32 s0, s0, s50
	s_add_u32 s68, s44, 0x80
	s_addc_u32 s69, s45, 0
	s_mov_b32 m0, s0
	ds_read_b128 v[180:183], v147 offset:49152
	ds_read_b128 v[184:187], v147 offset:50176
	ds_read_b128 v[188:191], v147 offset:51200
	ds_read_b128 v[218:221], v147 offset:52224
	ds_read_b128 v[222:225], v147 offset:53248
	ds_read_b128 v[226:229], v147 offset:54272
	ds_read_b128 v[230:233], v147 offset:55296
	ds_read_b128 v[234:237], v147 offset:56320
	global_load_lds_dwordx4 v134, s[68:69]
	s_add_i32 m0, s0, 0x2000
	s_add_u32 s44, s44, 0x100080
	s_addc_u32 s45, s45, 0
	s_add_i32 s0, s67, s50
	global_load_lds_dwordx4 v130, s[68:69]
	s_sub_u32 s68, s46, 0xfff80
	s_subb_u32 s69, s47, 0
	s_mov_b32 m0, s0
	s_nop 0
	global_load_lds_dwordx4 v134, s[44:45]
	s_add_i32 m0, s0, 0x2000
	s_nop 0
	global_load_lds_dwordx4 v130, s[44:45]
	s_mov_b32 m0, s57
	s_nop 0
	global_load_lds_dwordx4 v136, s[68:69]
	s_mov_b32 m0, s58
	s_nop 0
	global_load_lds_dwordx4 v132, s[68:69]
	s_waitcnt vmcnt(8)
	s_waitcnt lgkmcnt(0)
	s_barrier
	s_setprio 1
	s_waitcnt lgkmcnt(0)
	v_mfma_f32_16x16x32_bf16 v[62:65], v[148:151], v[180:183], v[62:65]
	v_mfma_f32_16x16x32_bf16 v[58:61], v[156:159], v[180:183], v[58:61]
	v_mfma_f32_16x16x32_bf16 v[54:57], v[148:151], v[188:191], v[54:57]
	v_mfma_f32_16x16x32_bf16 v[46:49], v[156:159], v[188:191], v[46:49]
	v_mfma_f32_16x16x32_bf16 v[38:41], v[148:151], v[222:225], v[38:41]
	v_mfma_f32_16x16x32_bf16 v[30:33], v[156:159], v[222:225], v[30:33]
	v_mfma_f32_16x16x32_bf16 v[22:25], v[148:151], v[230:233], v[22:25]
	v_mfma_f32_16x16x32_bf16 v[14:17], v[156:159], v[230:233], v[14:17]
	v_mfma_f32_16x16x32_bf16 v[62:65], v[152:155], v[184:187], v[62:65]
	v_mfma_f32_16x16x32_bf16 v[58:61], v[160:163], v[184:187], v[58:61]
	v_mfma_f32_16x16x32_bf16 v[54:57], v[152:155], v[218:221], v[54:57]
	v_mfma_f32_16x16x32_bf16 v[46:49], v[160:163], v[218:221], v[46:49]
	v_mfma_f32_16x16x32_bf16 v[38:41], v[152:155], v[226:229], v[38:41]
	v_mfma_f32_16x16x32_bf16 v[30:33], v[160:163], v[226:229], v[30:33]
	v_mfma_f32_16x16x32_bf16 v[22:25], v[152:155], v[234:237], v[22:25]
	v_mfma_f32_16x16x32_bf16 v[14:17], v[160:163], v[234:237], v[14:17]
	s_setprio 0
	s_setprio 1
	v_mfma_f32_16x16x32_bf16 v[50:53], v[164:167], v[180:183], v[50:53]
	v_mfma_f32_16x16x32_bf16 v[42:45], v[172:175], v[180:183], v[42:45]
	v_mfma_f32_16x16x32_bf16 v[34:37], v[164:167], v[188:191], v[34:37]
	v_mfma_f32_16x16x32_bf16 v[26:29], v[172:175], v[188:191], v[26:29]
	v_mfma_f32_16x16x32_bf16 v[18:21], v[164:167], v[222:225], v[18:21]
	v_mfma_f32_16x16x32_bf16 v[10:13], v[172:175], v[222:225], v[10:13]
	v_mfma_f32_16x16x32_bf16 v[6:9], v[164:167], v[230:233], v[6:9]
	v_mfma_f32_16x16x32_bf16 v[2:5], v[172:175], v[230:233], v[2:5]
	v_mfma_f32_16x16x32_bf16 v[50:53], v[168:171], v[184:187], v[50:53]
	v_mfma_f32_16x16x32_bf16 v[42:45], v[176:179], v[184:187], v[42:45]
	v_mfma_f32_16x16x32_bf16 v[34:37], v[168:171], v[218:221], v[34:37]
	v_mfma_f32_16x16x32_bf16 v[26:29], v[176:179], v[218:221], v[26:29]
	v_mfma_f32_16x16x32_bf16 v[18:21], v[168:171], v[226:229], v[18:21]
	v_mfma_f32_16x16x32_bf16 v[10:13], v[176:179], v[226:229], v[10:13]
	v_mfma_f32_16x16x32_bf16 v[6:9], v[168:171], v[234:237], v[6:9]
	v_mfma_f32_16x16x32_bf16 v[2:5], v[176:179], v[234:237], v[2:5]
	s_setprio 0
	s_barrier
	s_add_i32 s66, s66, 2
	s_add_u32 s42, s42, 0x100
	s_addc_u32 s43, s43, 0
	s_add_u32 s64, s64, 0x100
	s_addc_u32 s65, s65, 0
	s_cmp_gt_u32 s66, 61
	s_cbranch_scc0 .LBB0_241
	s_and_b64 vcc, exec, s[6:7]
	s_cbranch_vccz .LBB0_244
	s_barrier

.LBB0_695:
	v_lshl_add_u32 v148, s6, 8, v150
	s_lshl_b32 s0, s4, 8
	v_or_b32_e32 v149, s0, v152
	v_mov_b32_e32 v181, 0
	v_lshlrev_b32_e32 v180, 11, v148
	v_lshl_add_u32 v180, v149, 1, v180
	v_lshl_add_u64 v[142:143], s[40:41], 0, v[180:181]
	v_lshlrev_b32_e32 v180, 2, v149
	v_lshl_add_u64 v[178:179], s[46:47], 0, v[180:181]
	global_load_dwordx4 v[154:157], v[178:179], off
	global_load_dwordx4 v[158:161], v[178:179], off offset:16
	global_load_dwordx4 v[162:165], v[178:179], off offset:512
	global_load_dwordx4 v[166:169], v[178:179], off offset:528
	s_add_i32 s4, s0, 0x2400
	s_ashr_i32 s0, s4, 9
	s_mul_hi_i32 s4, s0, 0x1100000
	s_mul_i32 s0, s0, 0x1100000
	s_add_u32 s58, s65, s0
	s_addc_u32 s59, s66, s4
	v_and_b32_e32 v180, 0x1ff, v149
	v_lshlrev_b32_e32 v180, 1, v180
	v_lshl_add_u32 v180, v148, 10, v180
	v_lshl_add_u64 v[144:145], s[58:59], 0, v[180:181]
	v_lshlrev_b32_e32 v180, 13, v148
	v_lshl_add_u32 v180, v149, 1, v180
	v_add_u32_e32 v180, 0x1000, v180
	v_lshl_add_u64 v[146:147], s[44:45], 0, v[180:181]
	global_load_dwordx4 v[170:173], v[142:143], off
	global_load_dwordx4 v[174:177], v[144:145], off
	s_waitcnt vmcnt(2)
	v_pk_add_f32 v[126:127], v[126:127], v[154:155]
	v_pk_add_f32 v[122:123], v[122:123], v[158:159]
	v_pk_add_f32 v[128:129], v[128:129], v[156:157]
	v_pk_add_f32 v[124:125], v[124:125], v[160:161]
	v_pk_add_f32 v[118:119], v[118:119], v[162:163]
	v_pk_add_f32 v[114:115], v[114:115], v[166:167]
	v_pk_add_f32 v[120:121], v[120:121], v[164:165]
	v_pk_add_f32 v[116:117], v[116:117], v[168:169]
	v_pk_add_f32 v[110:111], v[110:111], v[154:155]
	v_pk_add_f32 v[106:107], v[106:107], v[158:159]
	v_pk_add_f32 v[112:113], v[112:113], v[156:157]
	v_pk_add_f32 v[108:109], v[108:109], v[160:161]
	v_pk_add_f32 v[102:103], v[102:103], v[162:163]
	v_pk_add_f32 v[98:99], v[98:99], v[166:167]
	v_pk_add_f32 v[104:105], v[104:105], v[164:165]
	v_pk_add_f32 v[100:101], v[100:101], v[168:169]
	v_pk_add_f32 v[94:95], v[94:95], v[154:155]
	v_pk_add_f32 v[90:91], v[90:91], v[158:159]
	v_pk_add_f32 v[96:97], v[96:97], v[156:157]
	v_pk_add_f32 v[92:93], v[92:93], v[160:161]
	v_pk_add_f32 v[86:87], v[86:87], v[162:163]
	v_pk_add_f32 v[82:83], v[82:83], v[166:167]
	v_pk_add_f32 v[88:89], v[88:89], v[164:165]
	v_pk_add_f32 v[84:85], v[84:85], v[168:169]
	v_pk_add_f32 v[78:79], v[78:79], v[154:155]
	v_pk_add_f32 v[74:75], v[74:75], v[158:159]
	v_pk_add_f32 v[80:81], v[80:81], v[156:157]
	v_pk_add_f32 v[76:77], v[76:77], v[160:161]
	v_pk_add_f32 v[70:71], v[70:71], v[162:163]
	v_pk_add_f32 v[66:67], v[66:67], v[166:167]
	v_pk_add_f32 v[72:73], v[72:73], v[164:165]
	v_pk_add_f32 v[68:69], v[68:69], v[168:169]
	v_pk_add_f32 v[62:63], v[62:63], v[154:155]
	v_pk_add_f32 v[58:59], v[58:59], v[158:159]
	v_pk_add_f32 v[64:65], v[64:65], v[156:157]
	v_pk_add_f32 v[60:61], v[60:61], v[160:161]
	v_pk_add_f32 v[54:55], v[54:55], v[162:163]
	v_pk_add_f32 v[50:51], v[50:51], v[166:167]
	v_pk_add_f32 v[56:57], v[56:57], v[164:165]
	v_pk_add_f32 v[52:53], v[52:53], v[168:169]
	v_pk_add_f32 v[46:47], v[46:47], v[154:155]
	v_pk_add_f32 v[42:43], v[42:43], v[158:159]
	v_pk_add_f32 v[48:49], v[48:49], v[156:157]
	v_pk_add_f32 v[44:45], v[44:45], v[160:161]
	v_pk_add_f32 v[38:39], v[38:39], v[162:163]
	v_pk_add_f32 v[34:35], v[34:35], v[166:167]
	v_pk_add_f32 v[40:41], v[40:41], v[164:165]
	v_pk_add_f32 v[36:37], v[36:37], v[168:169]
	v_pk_add_f32 v[30:31], v[30:31], v[154:155]
	v_pk_add_f32 v[26:27], v[26:27], v[158:159]
	v_pk_add_f32 v[32:33], v[32:33], v[156:157]
	v_pk_add_f32 v[28:29], v[28:29], v[160:161]
	v_pk_add_f32 v[22:23], v[22:23], v[162:163]
	v_pk_add_f32 v[18:19], v[18:19], v[166:167]
	v_pk_add_f32 v[24:25], v[24:25], v[164:165]
	v_pk_add_f32 v[20:21], v[20:21], v[168:169]
	v_pk_add_f32 v[14:15], v[14:15], v[154:155]
	v_pk_add_f32 v[10:11], v[10:11], v[158:159]
	v_pk_add_f32 v[16:17], v[16:17], v[156:157]
	v_pk_add_f32 v[12:13], v[12:13], v[160:161]
	v_pk_add_f32 v[6:7], v[6:7], v[162:163]
	v_pk_add_f32 v[2:3], v[2:3], v[166:167]
	v_pk_add_f32 v[8:9], v[8:9], v[164:165]
	v_pk_add_f32 v[4:5], v[4:5], v[168:169]
	global_load_dwordx4 v[154:157], v[142:143], off offset:256
	global_load_dwordx4 v[158:161], v[144:145], off offset:256
	s_mov_b64 s[58:59], 0x8000
	v_lshl_add_u64 v[142:143], v[142:143], 0, s[58:59]
	s_mov_b64 s[58:59], 0x4000
	v_lshl_add_u64 v[144:145], v[144:145], 0, s[58:59]
	global_load_dwordx4 v[162:165], v[142:143], off
	global_load_dwordx4 v[166:169], v[144:145], off
	s_waitcnt vmcnt(4)
	v_lshlrev_b32_e32 v178, 16, v170
	v_and_b32_e32 v170, 0xffff0000, v170
	v_lshlrev_b32_e32 v179, 16, v174
	v_and_b32_e32 v174, 0xffff0000, v174
	v_mul_f32_e32 v126, 0xbfb8aa3b, v126
	v_mul_f32_e32 v127, 0xbfb8aa3b, v127
	v_mul_f32_e32 v180, 0xbfb8aa3b, v179
	v_mul_f32_e32 v181, 0xbfb8aa3b, v174
	v_exp_f32_e32 v126, v126
	v_exp_f32_e32 v127, v127
	v_exp_f32_e32 v180, v180
	v_exp_f32_e32 v181, v181
	v_add_f32_e32 v126, 1.0, v126
	v_add_f32_e32 v127, 1.0, v127
	v_add_f32_e32 v180, 1.0, v180
	v_add_f32_e32 v181, 1.0, v181
	v_rcp_f32_e32 v126, v126
	v_rcp_f32_e32 v127, v127
	v_rcp_f32_e32 v180, v180
	v_rcp_f32_e32 v181, v181
	v_mul_f32_e32 v126, v126, v178
	v_mul_f32_e32 v127, v127, v170
	v_mul_f32_e32 v180, v180, v179
	v_mul_f32_e32 v181, v181, v174
	v_mul_f32_e32 v126, v126, v180
	v_mul_f32_e32 v127, v127, v181
	v_lshlrev_b32_e32 v178, 16, v171
	v_and_b32_e32 v171, 0xffff0000, v171
	v_lshlrev_b32_e32 v179, 16, v175
	v_and_b32_e32 v175, 0xffff0000, v175
	v_mul_f32_e32 v128, 0xbfb8aa3b, v128
	v_mul_f32_e32 v129, 0xbfb8aa3b, v129
	v_mul_f32_e32 v180, 0xbfb8aa3b, v179
	v_mul_f32_e32 v181, 0xbfb8aa3b, v175
	v_exp_f32_e32 v128, v128
	v_exp_f32_e32 v129, v129
	v_exp_f32_e32 v180, v180
	v_exp_f32_e32 v181, v181
	v_add_f32_e32 v128, 1.0, v128
	v_add_f32_e32 v129, 1.0, v129
	v_add_f32_e32 v180, 1.0, v180
	v_add_f32_e32 v181, 1.0, v181
	v_rcp_f32_e32 v128, v128
	v_rcp_f32_e32 v129, v129
	v_rcp_f32_e32 v180, v180
	v_rcp_f32_e32 v181, v181
	v_mul_f32_e32 v128, v128, v178
	v_mul_f32_e32 v129, v129, v171
	v_mul_f32_e32 v180, v180, v179
	v_mul_f32_e32 v181, v181, v175
	v_mul_f32_e32 v128, v128, v180
	v_mul_f32_e32 v129, v129, v181
	v_lshlrev_b32_e32 v178, 16, v172
	v_and_b32_e32 v172, 0xffff0000, v172
	v_lshlrev_b32_e32 v179, 16, v176
	v_and_b32_e32 v176, 0xffff0000, v176
	v_mul_f32_e32 v122, 0xbfb8aa3b, v122
	v_mul_f32_e32 v123, 0xbfb8aa3b, v123
	v_mul_f32_e32 v180, 0xbfb8aa3b, v179
	v_mul_f32_e32 v181, 0xbfb8aa3b, v176
	v_exp_f32_e32 v122, v122
	v_exp_f32_e32 v123, v123
	v_exp_f32_e32 v180, v180
	v_exp_f32_e32 v181, v181
	v_add_f32_e32 v122, 1.0, v122
	v_add_f32_e32 v123, 1.0, v123
	v_add_f32_e32 v180, 1.0, v180
	v_add_f32_e32 v181, 1.0, v181
	v_rcp_f32_e32 v122, v122
	v_rcp_f32_e32 v123, v123
	v_rcp_f32_e32 v180, v180
	v_rcp_f32_e32 v181, v181
	v_mul_f32_e32 v122, v122, v178
	v_mul_f32_e32 v123, v123, v172
	v_mul_f32_e32 v180, v180, v179
	v_mul_f32_e32 v181, v181, v176
	v_mul_f32_e32 v122, v122, v180
	v_mul_f32_e32 v123, v123, v181
	v_lshlrev_b32_e32 v178, 16, v173
	v_and_b32_e32 v173, 0xffff0000, v173
	v_lshlrev_b32_e32 v179, 16, v177
	v_and_b32_e32 v177, 0xffff0000, v177
	v_mul_f32_e32 v124, 0xbfb8aa3b, v124
	v_mul_f32_e32 v125, 0xbfb8aa3b, v125
	v_mul_f32_e32 v180, 0xbfb8aa3b, v179
	v_mul_f32_e32 v181, 0xbfb8aa3b, v177
	v_exp_f32_e32 v124, v124
	v_exp_f32_e32 v125, v125
	v_exp_f32_e32 v180, v180
	v_exp_f32_e32 v181, v181
	v_add_f32_e32 v124, 1.0, v124
	v_add_f32_e32 v125, 1.0, v125
	v_add_f32_e32 v180, 1.0, v180
	v_add_f32_e32 v181, 1.0, v181
	v_rcp_f32_e32 v124, v124
	v_rcp_f32_e32 v125, v125
	v_rcp_f32_e32 v180, v180
	v_rcp_f32_e32 v181, v181
	v_mul_f32_e32 v124, v124, v178
	v_mul_f32_e32 v125, v125, v173
	v_mul_f32_e32 v180, v180, v179
	v_mul_f32_e32 v181, v181, v177
	v_mul_f32_e32 v124, v124, v180
	v_mul_f32_e32 v125, v125, v181
	v_cvt_pk_bf16_f32 v126, v126, v127
	v_cvt_pk_bf16_f32 v127, v128, v129
	v_cvt_pk_bf16_f32 v128, v122, v123
	v_cvt_pk_bf16_f32 v129, v124, v125
	global_store_dwordx4 v[146:147], v[126:129], off
	global_load_dwordx4 v[170:173], v[142:143], off offset:256
	global_load_dwordx4 v[174:177], v[144:145], off offset:256
	s_waitcnt vmcnt(5)
	v_lshlrev_b32_e32 v178, 16, v154
	v_and_b32_e32 v154, 0xffff0000, v154
	v_lshlrev_b32_e32 v179, 16, v158
	v_and_b32_e32 v158, 0xffff0000, v158
	v_mul_f32_e32 v118, 0xbfb8aa3b, v118
	v_mul_f32_e32 v119, 0xbfb8aa3b, v119
	v_mul_f32_e32 v180, 0xbfb8aa3b, v179
	v_mul_f32_e32 v181, 0xbfb8aa3b, v158
	v_exp_f32_e32 v118, v118
	v_exp_f32_e32 v119, v119
	v_exp_f32_e32 v180, v180
	v_exp_f32_e32 v181, v181
	v_add_f32_e32 v118, 1.0, v118
	v_add_f32_e32 v119, 1.0, v119
	v_add_f32_e32 v180, 1.0, v180
	v_add_f32_e32 v181, 1.0, v181
	v_rcp_f32_e32 v118, v118
	v_rcp_f32_e32 v119, v119
	v_rcp_f32_e32 v180, v180
	v_rcp_f32_e32 v181, v181
	v_mul_f32_e32 v118, v118, v178
	v_mul_f32_e32 v119, v119, v154
	v_mul_f32_e32 v180, v180, v179
	v_mul_f32_e32 v181, v181, v158
	v_mul_f32_e32 v118, v118, v180
	v_mul_f32_e32 v119, v119, v181
	v_lshlrev_b32_e32 v178, 16, v155
	v_and_b32_e32 v155, 0xffff0000, v155
	v_lshlrev_b32_e32 v179, 16, v159
	v_and_b32_e32 v159, 0xffff0000, v159
	v_mul_f32_e32 v120, 0xbfb8aa3b, v120
	v_mul_f32_e32 v121, 0xbfb8aa3b, v121
	v_mul_f32_e32 v180, 0xbfb8aa3b, v179
	v_mul_f32_e32 v181, 0xbfb8aa3b, v159
	v_exp_f32_e32 v120, v120
	v_exp_f32_e32 v121, v121
	v_exp_f32_e32 v180, v180
	v_exp_f32_e32 v181, v181
	v_add_f32_e32 v120, 1.0, v120
	v_add_f32_e32 v121, 1.0, v121
	v_add_f32_e32 v180, 1.0, v180
	v_add_f32_e32 v181, 1.0, v181
	v_rcp_f32_e32 v120, v120
	v_rcp_f32_e32 v121, v121
	v_rcp_f32_e32 v180, v180
	v_rcp_f32_e32 v181, v181
	v_mul_f32_e32 v120, v120, v178
	v_mul_f32_e32 v121, v121, v155
	v_mul_f32_e32 v180, v180, v179
	v_mul_f32_e32 v181, v181, v159
	v_mul_f32_e32 v120, v120, v180
	v_mul_f32_e32 v121, v121, v181
	v_lshlrev_b32_e32 v178, 16, v156
	v_and_b32_e32 v156, 0xffff0000, v156
	v_lshlrev_b32_e32 v179, 16, v160
	v_and_b32_e32 v160, 0xffff0000, v160
	v_mul_f32_e32 v114, 0xbfb8aa3b, v114
	v_mul_f32_e32 v115, 0xbfb8aa3b, v115
	v_mul_f32_e32 v180, 0xbfb8aa3b, v179
	v_mul_f32_e32 v181, 0xbfb8aa3b, v160
	v_exp_f32_e32 v114, v114
	v_exp_f32_e32 v115, v115
	v_exp_f32_e32 v180, v180
	v_exp_f32_e32 v181, v181
	v_add_f32_e32 v114, 1.0, v114
	v_add_f32_e32 v115, 1.0, v115
	v_add_f32_e32 v180, 1.0, v180
	v_add_f32_e32 v181, 1.0, v181
	v_rcp_f32_e32 v114, v114
	v_rcp_f32_e32 v115, v115
	v_rcp_f32_e32 v180, v180
	v_rcp_f32_e32 v181, v181
	v_mul_f32_e32 v114, v114, v178
	v_mul_f32_e32 v115, v115, v156
	v_mul_f32_e32 v180, v180, v179
	v_mul_f32_e32 v181, v181, v160
	v_mul_f32_e32 v114, v114, v180
	v_mul_f32_e32 v115, v115, v181
	v_lshlrev_b32_e32 v178, 16, v157
	v_and_b32_e32 v157, 0xffff0000, v157
	v_lshlrev_b32_e32 v179, 16, v161
	v_and_b32_e32 v161, 0xffff0000, v161
	v_mul_f32_e32 v116, 0xbfb8aa3b, v116
	v_mul_f32_e32 v117, 0xbfb8aa3b, v117
	v_mul_f32_e32 v180, 0xbfb8aa3b, v179
	v_mul_f32_e32 v181, 0xbfb8aa3b, v161
	v_exp_f32_e32 v116, v116
	v_exp_f32_e32 v117, v117
	v_exp_f32_e32 v180, v180
	v_exp_f32_e32 v181, v181
	v_add_f32_e32 v116, 1.0, v116
	v_add_f32_e32 v117, 1.0, v117
	v_add_f32_e32 v180, 1.0, v180
	v_add_f32_e32 v181, 1.0, v181
	v_rcp_f32_e32 v116, v116
	v_rcp_f32_e32 v117, v117
	v_rcp_f32_e32 v180, v180
	v_rcp_f32_e32 v181, v181
	v_mul_f32_e32 v116, v116, v178
	v_mul_f32_e32 v117, v117, v157
	v_mul_f32_e32 v180, v180, v179
	v_mul_f32_e32 v181, v181, v161
	v_mul_f32_e32 v116, v116, v180
	v_mul_f32_e32 v117, v117, v181
	v_cvt_pk_bf16_f32 v118, v118, v119
	v_cvt_pk_bf16_f32 v119, v120, v121
	v_cvt_pk_bf16_f32 v120, v114, v115
	v_cvt_pk_bf16_f32 v121, v116, v117
	global_store_dwordx4 v[146:147], v[118:121], off offset:256
	s_mov_b64 s[58:59], 0x20000
	v_lshl_add_u64 v[146:147], v[146:147], 0, s[58:59]
	s_mov_b64 s[58:59], 0x8000
	v_lshl_add_u64 v[142:143], v[142:143], 0, s[58:59]
	s_mov_b64 s[58:59], 0x4000
	v_lshl_add_u64 v[144:145], v[144:145], 0, s[58:59]
	global_load_dwordx4 v[154:157], v[142:143], off
	global_load_dwordx4 v[158:161], v[144:145], off
	s_waitcnt vmcnt(6)
	v_lshlrev_b32_e32 v178, 16, v162
	v_and_b32_e32 v162, 0xffff0000, v162
	v_lshlrev_b32_e32 v179, 16, v166
	v_and_b32_e32 v166, 0xffff0000, v166
	v_mul_f32_e32 v110, 0xbfb8aa3b, v110
	v_mul_f32_e32 v111, 0xbfb8aa3b, v111
	v_mul_f32_e32 v180, 0xbfb8aa3b, v179
	v_mul_f32_e32 v181, 0xbfb8aa3b, v166
	v_exp_f32_e32 v110, v110
	v_exp_f32_e32 v111, v111
	v_exp_f32_e32 v180, v180
	v_exp_f32_e32 v181, v181
	v_add_f32_e32 v110, 1.0, v110
	v_add_f32_e32 v111, 1.0, v111
	v_add_f32_e32 v180, 1.0, v180
	v_add_f32_e32 v181, 1.0, v181
	v_rcp_f32_e32 v110, v110
	v_rcp_f32_e32 v111, v111
	v_rcp_f32_e32 v180, v180
	v_rcp_f32_e32 v181, v181
	v_mul_f32_e32 v110, v110, v178
	v_mul_f32_e32 v111, v111, v162
	v_mul_f32_e32 v180, v180, v179
	v_mul_f32_e32 v181, v181, v166
	v_mul_f32_e32 v110, v110, v180
	v_mul_f32_e32 v111, v111, v181
	v_lshlrev_b32_e32 v178, 16, v163
	v_and_b32_e32 v163, 0xffff0000, v163
	v_lshlrev_b32_e32 v179, 16, v167
	v_and_b32_e32 v167, 0xffff0000, v167
	v_mul_f32_e32 v112, 0xbfb8aa3b, v112
	v_mul_f32_e32 v113, 0xbfb8aa3b, v113
	v_mul_f32_e32 v180, 0xbfb8aa3b, v179
	v_mul_f32_e32 v181, 0xbfb8aa3b, v167
	v_exp_f32_e32 v112, v112
	v_exp_f32_e32 v113, v113
	v_exp_f32_e32 v180, v180
	v_exp_f32_e32 v181, v181
	v_add_f32_e32 v112, 1.0, v112
	v_add_f32_e32 v113, 1.0, v113
	v_add_f32_e32 v180, 1.0, v180
	v_add_f32_e32 v181, 1.0, v181
	v_rcp_f32_e32 v112, v112
	v_rcp_f32_e32 v113, v113
	v_rcp_f32_e32 v180, v180
	v_rcp_f32_e32 v181, v181
	v_mul_f32_e32 v112, v112, v178
	v_mul_f32_e32 v113, v113, v163
	v_mul_f32_e32 v180, v180, v179
	v_mul_f32_e32 v181, v181, v167
	v_mul_f32_e32 v112, v112, v180
	v_mul_f32_e32 v113, v113, v181
	v_lshlrev_b32_e32 v178, 16, v164
	v_and_b32_e32 v164, 0xffff0000, v164
	v_lshlrev_b32_e32 v179, 16, v168
	v_and_b32_e32 v168, 0xffff0000, v168
	v_mul_f32_e32 v106, 0xbfb8aa3b, v106
	v_mul_f32_e32 v107, 0xbfb8aa3b, v107
	v_mul_f32_e32 v180, 0xbfb8aa3b, v179
	v_mul_f32_e32 v181, 0xbfb8aa3b, v168
	v_exp_f32_e32 v106, v106
	v_exp_f32_e32 v107, v107
	v_exp_f32_e32 v180, v180
	v_exp_f32_e32 v181, v181
	v_add_f32_e32 v106, 1.0, v106
	v_add_f32_e32 v107, 1.0, v107
	v_add_f32_e32 v180, 1.0, v180
	v_add_f32_e32 v181, 1.0, v181
	v_rcp_f32_e32 v106, v106
	v_rcp_f32_e32 v107, v107
	v_rcp_f32_e32 v180, v180
	v_rcp_f32_e32 v181, v181
	v_mul_f32_e32 v106, v106, v178
	v_mul_f32_e32 v107, v107, v164
	v_mul_f32_e32 v180, v180, v179
	v_mul_f32_e32 v181, v181, v168
	v_mul_f32_e32 v106, v106, v180
	v_mul_f32_e32 v107, v107, v181
	v_lshlrev_b32_e32 v178, 16, v165
	v_and_b32_e32 v165, 0xffff0000, v165
	v_lshlrev_b32_e32 v179, 16, v169
	v_and_b32_e32 v169, 0xffff0000, v169
	v_mul_f32_e32 v108, 0xbfb8aa3b, v108
	v_mul_f32_e32 v109, 0xbfb8aa3b, v109
	v_mul_f32_e32 v180, 0xbfb8aa3b, v179
	v_mul_f32_e32 v181, 0xbfb8aa3b, v169
	v_exp_f32_e32 v108, v108
	v_exp_f32_e32 v109, v109
	v_exp_f32_e32 v180, v180
	v_exp_f32_e32 v181, v181
	v_add_f32_e32 v108, 1.0, v108
	v_add_f32_e32 v109, 1.0, v109
	v_add_f32_e32 v180, 1.0, v180
	v_add_f32_e32 v181, 1.0, v181
	v_rcp_f32_e32 v108, v108
	v_rcp_f32_e32 v109, v109
	v_rcp_f32_e32 v180, v180
	v_rcp_f32_e32 v181, v181
	v_mul_f32_e32 v108, v108, v178
	v_mul_f32_e32 v109, v109, v165
	v_mul_f32_e32 v180, v180, v179
	v_mul_f32_e32 v181, v181, v169
	v_mul_f32_e32 v108, v108, v180
	v_mul_f32_e32 v109, v109, v181
	v_cvt_pk_bf16_f32 v110, v110, v111
	v_cvt_pk_bf16_f32 v111, v112, v113
	v_cvt_pk_bf16_f32 v112, v106, v107
	v_cvt_pk_bf16_f32 v113, v108, v109
	global_store_dwordx4 v[146:147], v[110:113], off
	global_load_dwordx4 v[162:165], v[142:143], off offset:256
	global_load_dwordx4 v[166:169], v[144:145], off offset:256
	s_waitcnt vmcnt(6)
	v_lshlrev_b32_e32 v178, 16, v170
	v_and_b32_e32 v170, 0xffff0000, v170
	v_lshlrev_b32_e32 v179, 16, v174
	v_and_b32_e32 v174, 0xffff0000, v174
	v_mul_f32_e32 v102, 0xbfb8aa3b, v102
	v_mul_f32_e32 v103, 0xbfb8aa3b, v103
	v_mul_f32_e32 v180, 0xbfb8aa3b, v179
	v_mul_f32_e32 v181, 0xbfb8aa3b, v174
	v_exp_f32_e32 v102, v102
	v_exp_f32_e32 v103, v103
	v_exp_f32_e32 v180, v180
	v_exp_f32_e32 v181, v181
	v_add_f32_e32 v102, 1.0, v102
	v_add_f32_e32 v103, 1.0, v103
	v_add_f32_e32 v180, 1.0, v180
	v_add_f32_e32 v181, 1.0, v181
	v_rcp_f32_e32 v102, v102
	v_rcp_f32_e32 v103, v103
	v_rcp_f32_e32 v180, v180
	v_rcp_f32_e32 v181, v181
	v_mul_f32_e32 v102, v102, v178
	v_mul_f32_e32 v103, v103, v170
	v_mul_f32_e32 v180, v180, v179
	v_mul_f32_e32 v181, v181, v174
	v_mul_f32_e32 v102, v102, v180
	v_mul_f32_e32 v103, v103, v181
	v_lshlrev_b32_e32 v178, 16, v171
	v_and_b32_e32 v171, 0xffff0000, v171
	v_lshlrev_b32_e32 v179, 16, v175
	v_and_b32_e32 v175, 0xffff0000, v175
	v_mul_f32_e32 v104, 0xbfb8aa3b, v104
	v_mul_f32_e32 v105, 0xbfb8aa3b, v105
	v_mul_f32_e32 v180, 0xbfb8aa3b, v179
	v_mul_f32_e32 v181, 0xbfb8aa3b, v175
	v_exp_f32_e32 v104, v104
	v_exp_f32_e32 v105, v105
	v_exp_f32_e32 v180, v180
	v_exp_f32_e32 v181, v181
	v_add_f32_e32 v104, 1.0, v104
	v_add_f32_e32 v105, 1.0, v105
	v_add_f32_e32 v180, 1.0, v180
	v_add_f32_e32 v181, 1.0, v181
	v_rcp_f32_e32 v104, v104
	v_rcp_f32_e32 v105, v105
	v_rcp_f32_e32 v180, v180
	v_rcp_f32_e32 v181, v181
	v_mul_f32_e32 v104, v104, v178
	v_mul_f32_e32 v105, v105, v171
	v_mul_f32_e32 v180, v180, v179
	v_mul_f32_e32 v181, v181, v175
	v_mul_f32_e32 v104, v104, v180
	v_mul_f32_e32 v105, v105, v181
	v_lshlrev_b32_e32 v178, 16, v172
	v_and_b32_e32 v172, 0xffff0000, v172
	v_lshlrev_b32_e32 v179, 16, v176
	v_and_b32_e32 v176, 0xffff0000, v176
	v_mul_f32_e32 v98, 0xbfb8aa3b, v98
	v_mul_f32_e32 v99, 0xbfb8aa3b, v99
	v_mul_f32_e32 v180, 0xbfb8aa3b, v179
	v_mul_f32_e32 v181, 0xbfb8aa3b, v176
	v_exp_f32_e32 v98, v98
	v_exp_f32_e32 v99, v99
	v_exp_f32_e32 v180, v180
	v_exp_f32_e32 v181, v181
	v_add_f32_e32 v98, 1.0, v98
	v_add_f32_e32 v99, 1.0, v99
	v_add_f32_e32 v180, 1.0, v180
	v_add_f32_e32 v181, 1.0, v181
	v_rcp_f32_e32 v98, v98
	v_rcp_f32_e32 v99, v99
	v_rcp_f32_e32 v180, v180
	v_rcp_f32_e32 v181, v181
	v_mul_f32_e32 v98, v98, v178
	v_mul_f32_e32 v99, v99, v172
	v_mul_f32_e32 v180, v180, v179
	v_mul_f32_e32 v181, v181, v176
	v_mul_f32_e32 v98, v98, v180
	v_mul_f32_e32 v99, v99, v181
	v_lshlrev_b32_e32 v178, 16, v173
	v_and_b32_e32 v173, 0xffff0000, v173
	v_lshlrev_b32_e32 v179, 16, v177
	v_and_b32_e32 v177, 0xffff0000, v177
	v_mul_f32_e32 v100, 0xbfb8aa3b, v100
	v_mul_f32_e32 v101, 0xbfb8aa3b, v101
	v_mul_f32_e32 v180, 0xbfb8aa3b, v179
	v_mul_f32_e32 v181, 0xbfb8aa3b, v177
	v_exp_f32_e32 v100, v100
	v_exp_f32_e32 v101, v101
	v_exp_f32_e32 v180, v180
	v_exp_f32_e32 v181, v181
	v_add_f32_e32 v100, 1.0, v100
	v_add_f32_e32 v101, 1.0, v101
	v_add_f32_e32 v180, 1.0, v180
	v_add_f32_e32 v181, 1.0, v181
	v_rcp_f32_e32 v100, v100
	v_rcp_f32_e32 v101, v101
	v_rcp_f32_e32 v180, v180
	v_rcp_f32_e32 v181, v181
	v_mul_f32_e32 v100, v100, v178
	v_mul_f32_e32 v101, v101, v173
	v_mul_f32_e32 v180, v180, v179
	v_mul_f32_e32 v181, v181, v177
	v_mul_f32_e32 v100, v100, v180
	v_mul_f32_e32 v101, v101, v181
	v_cvt_pk_bf16_f32 v102, v102, v103
	v_cvt_pk_bf16_f32 v103, v104, v105
	v_cvt_pk_bf16_f32 v104, v98, v99
	v_cvt_pk_bf16_f32 v105, v100, v101
	global_store_dwordx4 v[146:147], v[102:105], off offset:256
	s_mov_b64 s[58:59], 0x20000
	v_lshl_add_u64 v[146:147], v[146:147], 0, s[58:59]
	s_mov_b64 s[58:59], 0x8000
	v_lshl_add_u64 v[142:143], v[142:143], 0, s[58:59]
	s_mov_b64 s[58:59], 0x4000
	v_lshl_add_u64 v[144:145], v[144:145], 0, s[58:59]
	global_load_dwordx4 v[170:173], v[142:143], off
	global_load_dwordx4 v[174:177], v[144:145], off
	s_waitcnt vmcnt(6)
	v_lshlrev_b32_e32 v178, 16, v154
	v_and_b32_e32 v154, 0xffff0000, v154
	v_lshlrev_b32_e32 v179, 16, v158
	v_and_b32_e32 v158, 0xffff0000, v158
	v_mul_f32_e32 v94, 0xbfb8aa3b, v94
	v_mul_f32_e32 v95, 0xbfb8aa3b, v95
	v_mul_f32_e32 v180, 0xbfb8aa3b, v179
	v_mul_f32_e32 v181, 0xbfb8aa3b, v158
	v_exp_f32_e32 v94, v94
	v_exp_f32_e32 v95, v95
	v_exp_f32_e32 v180, v180
	v_exp_f32_e32 v181, v181
	v_add_f32_e32 v94, 1.0, v94
	v_add_f32_e32 v95, 1.0, v95
	v_add_f32_e32 v180, 1.0, v180
	v_add_f32_e32 v181, 1.0, v181
	v_rcp_f32_e32 v94, v94
	v_rcp_f32_e32 v95, v95
	v_rcp_f32_e32 v180, v180
	v_rcp_f32_e32 v181, v181
	v_mul_f32_e32 v94, v94, v178
	v_mul_f32_e32 v95, v95, v154
	v_mul_f32_e32 v180, v180, v179
	v_mul_f32_e32 v181, v181, v158
	v_mul_f32_e32 v94, v94, v180
	v_mul_f32_e32 v95, v95, v181
	v_lshlrev_b32_e32 v178, 16, v155
	v_and_b32_e32 v155, 0xffff0000, v155
	v_lshlrev_b32_e32 v179, 16, v159
	v_and_b32_e32 v159, 0xffff0000, v159
	v_mul_f32_e32 v96, 0xbfb8aa3b, v96
	v_mul_f32_e32 v97, 0xbfb8aa3b, v97
	v_mul_f32_e32 v180, 0xbfb8aa3b, v179
	v_mul_f32_e32 v181, 0xbfb8aa3b, v159
	v_exp_f32_e32 v96, v96
	v_exp_f32_e32 v97, v97
	v_exp_f32_e32 v180, v180
	v_exp_f32_e32 v181, v181
	v_add_f32_e32 v96, 1.0, v96
	v_add_f32_e32 v97, 1.0, v97
	v_add_f32_e32 v180, 1.0, v180
	v_add_f32_e32 v181, 1.0, v181
	v_rcp_f32_e32 v96, v96
	v_rcp_f32_e32 v97, v97
	v_rcp_f32_e32 v180, v180
	v_rcp_f32_e32 v181, v181
	v_mul_f32_e32 v96, v96, v178
	v_mul_f32_e32 v97, v97, v155
	v_mul_f32_e32 v180, v180, v179
	v_mul_f32_e32 v181, v181, v159
	v_mul_f32_e32 v96, v96, v180
	v_mul_f32_e32 v97, v97, v181
	v_lshlrev_b32_e32 v178, 16, v156
	v_and_b32_e32 v156, 0xffff0000, v156
	v_lshlrev_b32_e32 v179, 16, v160
	v_and_b32_e32 v160, 0xffff0000, v160
	v_mul_f32_e32 v90, 0xbfb8aa3b, v90
	v_mul_f32_e32 v91, 0xbfb8aa3b, v91
	v_mul_f32_e32 v180, 0xbfb8aa3b, v179
	v_mul_f32_e32 v181, 0xbfb8aa3b, v160
	v_exp_f32_e32 v90, v90
	v_exp_f32_e32 v91, v91
	v_exp_f32_e32 v180, v180
	v_exp_f32_e32 v181, v181
	v_add_f32_e32 v90, 1.0, v90
	v_add_f32_e32 v91, 1.0, v91
	v_add_f32_e32 v180, 1.0, v180
	v_add_f32_e32 v181, 1.0, v181
	v_rcp_f32_e32 v90, v90
	v_rcp_f32_e32 v91, v91
	v_rcp_f32_e32 v180, v180
	v_rcp_f32_e32 v181, v181
	v_mul_f32_e32 v90, v90, v178
	v_mul_f32_e32 v91, v91, v156
	v_mul_f32_e32 v180, v180, v179
	v_mul_f32_e32 v181, v181, v160
	v_mul_f32_e32 v90, v90, v180
	v_mul_f32_e32 v91, v91, v181
	v_lshlrev_b32_e32 v178, 16, v157
	v_and_b32_e32 v157, 0xffff0000, v157
	v_lshlrev_b32_e32 v179, 16, v161
	v_and_b32_e32 v161, 0xffff0000, v161
	v_mul_f32_e32 v92, 0xbfb8aa3b, v92
	v_mul_f32_e32 v93, 0xbfb8aa3b, v93
	v_mul_f32_e32 v180, 0xbfb8aa3b, v179
	v_mul_f32_e32 v181, 0xbfb8aa3b, v161
	v_exp_f32_e32 v92, v92
	v_exp_f32_e32 v93, v93
	v_exp_f32_e32 v180, v180
	v_exp_f32_e32 v181, v181
	v_add_f32_e32 v92, 1.0, v92
	v_add_f32_e32 v93, 1.0, v93
	v_add_f32_e32 v180, 1.0, v180
	v_add_f32_e32 v181, 1.0, v181
	v_rcp_f32_e32 v92, v92
	v_rcp_f32_e32 v93, v93
	v_rcp_f32_e32 v180, v180
	v_rcp_f32_e32 v181, v181
	v_mul_f32_e32 v92, v92, v178
	v_mul_f32_e32 v93, v93, v157
	v_mul_f32_e32 v180, v180, v179
	v_mul_f32_e32 v181, v181, v161
	v_mul_f32_e32 v92, v92, v180
	v_mul_f32_e32 v93, v93, v181
	v_cvt_pk_bf16_f32 v94, v94, v95
	v_cvt_pk_bf16_f32 v95, v96, v97
	v_cvt_pk_bf16_f32 v96, v90, v91
	v_cvt_pk_bf16_f32 v97, v92, v93
	global_store_dwordx4 v[146:147], v[94:97], off
	global_load_dwordx4 v[154:157], v[142:143], off offset:256
	global_load_dwordx4 v[158:161], v[144:145], off offset:256
	s_waitcnt vmcnt(6)
	v_lshlrev_b32_e32 v178, 16, v162
	v_and_b32_e32 v162, 0xffff0000, v162
	v_lshlrev_b32_e32 v179, 16, v166
	v_and_b32_e32 v166, 0xffff0000, v166
	v_mul_f32_e32 v86, 0xbfb8aa3b, v86
	v_mul_f32_e32 v87, 0xbfb8aa3b, v87
	v_mul_f32_e32 v180, 0xbfb8aa3b, v179
	v_mul_f32_e32 v181, 0xbfb8aa3b, v166
	v_exp_f32_e32 v86, v86
	v_exp_f32_e32 v87, v87
	v_exp_f32_e32 v180, v180
	v_exp_f32_e32 v181, v181
	v_add_f32_e32 v86, 1.0, v86
	v_add_f32_e32 v87, 1.0, v87
	v_add_f32_e32 v180, 1.0, v180
	v_add_f32_e32 v181, 1.0, v181
	v_rcp_f32_e32 v86, v86
	v_rcp_f32_e32 v87, v87
	v_rcp_f32_e32 v180, v180
	v_rcp_f32_e32 v181, v181
	v_mul_f32_e32 v86, v86, v178
	v_mul_f32_e32 v87, v87, v162
	v_mul_f32_e32 v180, v180, v179
	v_mul_f32_e32 v181, v181, v166
	v_mul_f32_e32 v86, v86, v180
	v_mul_f32_e32 v87, v87, v181
	v_lshlrev_b32_e32 v178, 16, v163
	v_and_b32_e32 v163, 0xffff0000, v163
	v_lshlrev_b32_e32 v179, 16, v167
	v_and_b32_e32 v167, 0xffff0000, v167
	v_mul_f32_e32 v88, 0xbfb8aa3b, v88
	v_mul_f32_e32 v89, 0xbfb8aa3b, v89
	v_mul_f32_e32 v180, 0xbfb8aa3b, v179
	v_mul_f32_e32 v181, 0xbfb8aa3b, v167
	v_exp_f32_e32 v88, v88
	v_exp_f32_e32 v89, v89
	v_exp_f32_e32 v180, v180
	v_exp_f32_e32 v181, v181
	v_add_f32_e32 v88, 1.0, v88
	v_add_f32_e32 v89, 1.0, v89
	v_add_f32_e32 v180, 1.0, v180
	v_add_f32_e32 v181, 1.0, v181
	v_rcp_f32_e32 v88, v88
	v_rcp_f32_e32 v89, v89
	v_rcp_f32_e32 v180, v180
	v_rcp_f32_e32 v181, v181
	v_mul_f32_e32 v88, v88, v178
	v_mul_f32_e32 v89, v89, v163
	v_mul_f32_e32 v180, v180, v179
	v_mul_f32_e32 v181, v181, v167
	v_mul_f32_e32 v88, v88, v180
	v_mul_f32_e32 v89, v89, v181
	v_lshlrev_b32_e32 v178, 16, v164
	v_and_b32_e32 v164, 0xffff0000, v164
	v_lshlrev_b32_e32 v179, 16, v168
	v_and_b32_e32 v168, 0xffff0000, v168
	v_mul_f32_e32 v82, 0xbfb8aa3b, v82
	v_mul_f32_e32 v83, 0xbfb8aa3b, v83
	v_mul_f32_e32 v180, 0xbfb8aa3b, v179
	v_mul_f32_e32 v181, 0xbfb8aa3b, v168
	v_exp_f32_e32 v82, v82
	v_exp_f32_e32 v83, v83
	v_exp_f32_e32 v180, v180
	v_exp_f32_e32 v181, v181
	v_add_f32_e32 v82, 1.0, v82
	v_add_f32_e32 v83, 1.0, v83
	v_add_f32_e32 v180, 1.0, v180
	v_add_f32_e32 v181, 1.0, v181
	v_rcp_f32_e32 v82, v82
	v_rcp_f32_e32 v83, v83
	v_rcp_f32_e32 v180, v180
	v_rcp_f32_e32 v181, v181
	v_mul_f32_e32 v82, v82, v178
	v_mul_f32_e32 v83, v83, v164
	v_mul_f32_e32 v180, v180, v179
	v_mul_f32_e32 v181, v181, v168
	v_mul_f32_e32 v82, v82, v180
	v_mul_f32_e32 v83, v83, v181
	v_lshlrev_b32_e32 v178, 16, v165
	v_and_b32_e32 v165, 0xffff0000, v165
	v_lshlrev_b32_e32 v179, 16, v169
	v_and_b32_e32 v169, 0xffff0000, v169
	v_mul_f32_e32 v84, 0xbfb8aa3b, v84
	v_mul_f32_e32 v85, 0xbfb8aa3b, v85
	v_mul_f32_e32 v180, 0xbfb8aa3b, v179
	v_mul_f32_e32 v181, 0xbfb8aa3b, v169
	v_exp_f32_e32 v84, v84
	v_exp_f32_e32 v85, v85
	v_exp_f32_e32 v180, v180
	v_exp_f32_e32 v181, v181
	v_add_f32_e32 v84, 1.0, v84
	v_add_f32_e32 v85, 1.0, v85
	v_add_f32_e32 v180, 1.0, v180
	v_add_f32_e32 v181, 1.0, v181
	v_rcp_f32_e32 v84, v84
	v_rcp_f32_e32 v85, v85
	v_rcp_f32_e32 v180, v180
	v_rcp_f32_e32 v181, v181
	v_mul_f32_e32 v84, v84, v178
	v_mul_f32_e32 v85, v85, v165
	v_mul_f32_e32 v180, v180, v179
	v_mul_f32_e32 v181, v181, v169
	v_mul_f32_e32 v84, v84, v180
	v_mul_f32_e32 v85, v85, v181
	v_cvt_pk_bf16_f32 v86, v86, v87
	v_cvt_pk_bf16_f32 v87, v88, v89
	v_cvt_pk_bf16_f32 v88, v82, v83
	v_cvt_pk_bf16_f32 v89, v84, v85
	global_store_dwordx4 v[146:147], v[86:89], off offset:256
	s_mov_b64 s[58:59], 0x20000
	v_lshl_add_u64 v[146:147], v[146:147], 0, s[58:59]
	s_mov_b64 s[58:59], 0x28000
	v_lshl_add_u64 v[142:143], v[142:143], 0, s[58:59]
	s_mov_b64 s[58:59], 0x14000
	v_lshl_add_u64 v[144:145], v[144:145], 0, s[58:59]
	global_load_dwordx4 v[162:165], v[142:143], off
	global_load_dwordx4 v[166:169], v[144:145], off
	s_waitcnt vmcnt(6)
	v_lshlrev_b32_e32 v178, 16, v170
	v_and_b32_e32 v170, 0xffff0000, v170
	v_lshlrev_b32_e32 v179, 16, v174
	v_and_b32_e32 v174, 0xffff0000, v174
	v_mul_f32_e32 v78, 0xbfb8aa3b, v78
	v_mul_f32_e32 v79, 0xbfb8aa3b, v79
	v_mul_f32_e32 v180, 0xbfb8aa3b, v179
	v_mul_f32_e32 v181, 0xbfb8aa3b, v174
	v_exp_f32_e32 v78, v78
	v_exp_f32_e32 v79, v79
	v_exp_f32_e32 v180, v180
	v_exp_f32_e32 v181, v181
	v_add_f32_e32 v78, 1.0, v78
	v_add_f32_e32 v79, 1.0, v79
	v_add_f32_e32 v180, 1.0, v180
	v_add_f32_e32 v181, 1.0, v181
	v_rcp_f32_e32 v78, v78
	v_rcp_f32_e32 v79, v79
	v_rcp_f32_e32 v180, v180
	v_rcp_f32_e32 v181, v181
	v_mul_f32_e32 v78, v78, v178
	v_mul_f32_e32 v79, v79, v170
	v_mul_f32_e32 v180, v180, v179
	v_mul_f32_e32 v181, v181, v174
	v_mul_f32_e32 v78, v78, v180
	v_mul_f32_e32 v79, v79, v181
	v_lshlrev_b32_e32 v178, 16, v171
	v_and_b32_e32 v171, 0xffff0000, v171
	v_lshlrev_b32_e32 v179, 16, v175
	v_and_b32_e32 v175, 0xffff0000, v175
	v_mul_f32_e32 v80, 0xbfb8aa3b, v80
	v_mul_f32_e32 v81, 0xbfb8aa3b, v81
	v_mul_f32_e32 v180, 0xbfb8aa3b, v179
	v_mul_f32_e32 v181, 0xbfb8aa3b, v175
	v_exp_f32_e32 v80, v80
	v_exp_f32_e32 v81, v81
	v_exp_f32_e32 v180, v180
	v_exp_f32_e32 v181, v181
	v_add_f32_e32 v80, 1.0, v80
	v_add_f32_e32 v81, 1.0, v81
	v_add_f32_e32 v180, 1.0, v180
	v_add_f32_e32 v181, 1.0, v181
	v_rcp_f32_e32 v80, v80
	v_rcp_f32_e32 v81, v81
	v_rcp_f32_e32 v180, v180
	v_rcp_f32_e32 v181, v181
	v_mul_f32_e32 v80, v80, v178
	v_mul_f32_e32 v81, v81, v171
	v_mul_f32_e32 v180, v180, v179
	v_mul_f32_e32 v181, v181, v175
	v_mul_f32_e32 v80, v80, v180
	v_mul_f32_e32 v81, v81, v181
	v_lshlrev_b32_e32 v178, 16, v172
	v_and_b32_e32 v172, 0xffff0000, v172
	v_lshlrev_b32_e32 v179, 16, v176
	v_and_b32_e32 v176, 0xffff0000, v176
	v_mul_f32_e32 v74, 0xbfb8aa3b, v74
	v_mul_f32_e32 v75, 0xbfb8aa3b, v75
	v_mul_f32_e32 v180, 0xbfb8aa3b, v179
	v_mul_f32_e32 v181, 0xbfb8aa3b, v176
	v_exp_f32_e32 v74, v74
	v_exp_f32_e32 v75, v75
	v_exp_f32_e32 v180, v180
	v_exp_f32_e32 v181, v181
	v_add_f32_e32 v74, 1.0, v74
	v_add_f32_e32 v75, 1.0, v75
	v_add_f32_e32 v180, 1.0, v180
	v_add_f32_e32 v181, 1.0, v181
	v_rcp_f32_e32 v74, v74
	v_rcp_f32_e32 v75, v75
	v_rcp_f32_e32 v180, v180
	v_rcp_f32_e32 v181, v181
	v_mul_f32_e32 v74, v74, v178
	v_mul_f32_e32 v75, v75, v172
	v_mul_f32_e32 v180, v180, v179
	v_mul_f32_e32 v181, v181, v176
	v_mul_f32_e32 v74, v74, v180
	v_mul_f32_e32 v75, v75, v181
	v_lshlrev_b32_e32 v178, 16, v173
	v_and_b32_e32 v173, 0xffff0000, v173
	v_lshlrev_b32_e32 v179, 16, v177
	v_and_b32_e32 v177, 0xffff0000, v177
	v_mul_f32_e32 v76, 0xbfb8aa3b, v76
	v_mul_f32_e32 v77, 0xbfb8aa3b, v77
	v_mul_f32_e32 v180, 0xbfb8aa3b, v179
	v_mul_f32_e32 v181, 0xbfb8aa3b, v177
	v_exp_f32_e32 v76, v76
	v_exp_f32_e32 v77, v77
	v_exp_f32_e32 v180, v180
	v_exp_f32_e32 v181, v181
	v_add_f32_e32 v76, 1.0, v76
	v_add_f32_e32 v77, 1.0, v77
	v_add_f32_e32 v180, 1.0, v180
	v_add_f32_e32 v181, 1.0, v181
	v_rcp_f32_e32 v76, v76
	v_rcp_f32_e32 v77, v77
	v_rcp_f32_e32 v180, v180
	v_rcp_f32_e32 v181, v181
	v_mul_f32_e32 v76, v76, v178
	v_mul_f32_e32 v77, v77, v173
	v_mul_f32_e32 v180, v180, v179
	v_mul_f32_e32 v181, v181, v177
	v_mul_f32_e32 v76, v76, v180
	v_mul_f32_e32 v77, v77, v181
	v_cvt_pk_bf16_f32 v78, v78, v79
	v_cvt_pk_bf16_f32 v79, v80, v81
	v_cvt_pk_bf16_f32 v80, v74, v75
	v_cvt_pk_bf16_f32 v81, v76, v77
	global_store_dwordx4 v[146:147], v[78:81], off
	global_load_dwordx4 v[170:173], v[142:143], off offset:256
	global_load_dwordx4 v[174:177], v[144:145], off offset:256
	s_waitcnt vmcnt(6)
	v_lshlrev_b32_e32 v178, 16, v154
	v_and_b32_e32 v154, 0xffff0000, v154
	v_lshlrev_b32_e32 v179, 16, v158
	v_and_b32_e32 v158, 0xffff0000, v158
	v_mul_f32_e32 v70, 0xbfb8aa3b, v70
	v_mul_f32_e32 v71, 0xbfb8aa3b, v71
	v_mul_f32_e32 v180, 0xbfb8aa3b, v179
	v_mul_f32_e32 v181, 0xbfb8aa3b, v158
	v_exp_f32_e32 v70, v70
	v_exp_f32_e32 v71, v71
	v_exp_f32_e32 v180, v180
	v_exp_f32_e32 v181, v181
	v_add_f32_e32 v70, 1.0, v70
	v_add_f32_e32 v71, 1.0, v71
	v_add_f32_e32 v180, 1.0, v180
	v_add_f32_e32 v181, 1.0, v181
	v_rcp_f32_e32 v70, v70
	v_rcp_f32_e32 v71, v71
	v_rcp_f32_e32 v180, v180
	v_rcp_f32_e32 v181, v181
	v_mul_f32_e32 v70, v70, v178
	v_mul_f32_e32 v71, v71, v154
	v_mul_f32_e32 v180, v180, v179
	v_mul_f32_e32 v181, v181, v158
	v_mul_f32_e32 v70, v70, v180
	v_mul_f32_e32 v71, v71, v181
	v_lshlrev_b32_e32 v178, 16, v155
	v_and_b32_e32 v155, 0xffff0000, v155
	v_lshlrev_b32_e32 v179, 16, v159
	v_and_b32_e32 v159, 0xffff0000, v159
	v_mul_f32_e32 v72, 0xbfb8aa3b, v72
	v_mul_f32_e32 v73, 0xbfb8aa3b, v73
	v_mul_f32_e32 v180, 0xbfb8aa3b, v179
	v_mul_f32_e32 v181, 0xbfb8aa3b, v159
	v_exp_f32_e32 v72, v72
	v_exp_f32_e32 v73, v73
	v_exp_f32_e32 v180, v180
	v_exp_f32_e32 v181, v181
	v_add_f32_e32 v72, 1.0, v72
	v_add_f32_e32 v73, 1.0, v73
	v_add_f32_e32 v180, 1.0, v180
	v_add_f32_e32 v181, 1.0, v181
	v_rcp_f32_e32 v72, v72
	v_rcp_f32_e32 v73, v73
	v_rcp_f32_e32 v180, v180
	v_rcp_f32_e32 v181, v181
	v_mul_f32_e32 v72, v72, v178
	v_mul_f32_e32 v73, v73, v155
	v_mul_f32_e32 v180, v180, v179
	v_mul_f32_e32 v181, v181, v159
	v_mul_f32_e32 v72, v72, v180
	v_mul_f32_e32 v73, v73, v181
	v_lshlrev_b32_e32 v178, 16, v156
	v_and_b32_e32 v156, 0xffff0000, v156
	v_lshlrev_b32_e32 v179, 16, v160
	v_and_b32_e32 v160, 0xffff0000, v160
	v_mul_f32_e32 v66, 0xbfb8aa3b, v66
	v_mul_f32_e32 v67, 0xbfb8aa3b, v67
	v_mul_f32_e32 v180, 0xbfb8aa3b, v179
	v_mul_f32_e32 v181, 0xbfb8aa3b, v160
	v_exp_f32_e32 v66, v66
	v_exp_f32_e32 v67, v67
	v_exp_f32_e32 v180, v180
	v_exp_f32_e32 v181, v181
	v_add_f32_e32 v66, 1.0, v66
	v_add_f32_e32 v67, 1.0, v67
	v_add_f32_e32 v180, 1.0, v180
	v_add_f32_e32 v181, 1.0, v181
	v_rcp_f32_e32 v66, v66
	v_rcp_f32_e32 v67, v67
	v_rcp_f32_e32 v180, v180
	v_rcp_f32_e32 v181, v181
	v_mul_f32_e32 v66, v66, v178
	v_mul_f32_e32 v67, v67, v156
	v_mul_f32_e32 v180, v180, v179
	v_mul_f32_e32 v181, v181, v160
	v_mul_f32_e32 v66, v66, v180
	v_mul_f32_e32 v67, v67, v181
	v_lshlrev_b32_e32 v178, 16, v157
	v_and_b32_e32 v157, 0xffff0000, v157
	v_lshlrev_b32_e32 v179, 16, v161
	v_and_b32_e32 v161, 0xffff0000, v161
	v_mul_f32_e32 v68, 0xbfb8aa3b, v68
	v_mul_f32_e32 v69, 0xbfb8aa3b, v69
	v_mul_f32_e32 v180, 0xbfb8aa3b, v179
	v_mul_f32_e32 v181, 0xbfb8aa3b, v161
	v_exp_f32_e32 v68, v68
	v_exp_f32_e32 v69, v69
	v_exp_f32_e32 v180, v180
	v_exp_f32_e32 v181, v181
	v_add_f32_e32 v68, 1.0, v68
	v_add_f32_e32 v69, 1.0, v69
	v_add_f32_e32 v180, 1.0, v180
	v_add_f32_e32 v181, 1.0, v181
	v_rcp_f32_e32 v68, v68
	v_rcp_f32_e32 v69, v69
	v_rcp_f32_e32 v180, v180
	v_rcp_f32_e32 v181, v181
	v_mul_f32_e32 v68, v68, v178
	v_mul_f32_e32 v69, v69, v157
	v_mul_f32_e32 v180, v180, v179
	v_mul_f32_e32 v181, v181, v161
	v_mul_f32_e32 v68, v68, v180
	v_mul_f32_e32 v69, v69, v181
	v_cvt_pk_bf16_f32 v70, v70, v71
	v_cvt_pk_bf16_f32 v71, v72, v73
	v_cvt_pk_bf16_f32 v72, v66, v67
	v_cvt_pk_bf16_f32 v73, v68, v69
	global_store_dwordx4 v[146:147], v[70:73], off offset:256
	s_mov_b64 s[58:59], 0xa0000
	v_lshl_add_u64 v[146:147], v[146:147], 0, s[58:59]
	s_mov_b64 s[58:59], 0x8000
	v_lshl_add_u64 v[142:143], v[142:143], 0, s[58:59]
	s_mov_b64 s[58:59], 0x4000
	v_lshl_add_u64 v[144:145], v[144:145], 0, s[58:59]
	global_load_dwordx4 v[154:157], v[142:143], off
	global_load_dwordx4 v[158:161], v[144:145], off
	s_waitcnt vmcnt(6)
	v_lshlrev_b32_e32 v178, 16, v162
	v_and_b32_e32 v162, 0xffff0000, v162
	v_lshlrev_b32_e32 v179, 16, v166
	v_and_b32_e32 v166, 0xffff0000, v166
	v_mul_f32_e32 v62, 0xbfb8aa3b, v62
	v_mul_f32_e32 v63, 0xbfb8aa3b, v63
	v_mul_f32_e32 v180, 0xbfb8aa3b, v179
	v_mul_f32_e32 v181, 0xbfb8aa3b, v166
	v_exp_f32_e32 v62, v62
	v_exp_f32_e32 v63, v63
	v_exp_f32_e32 v180, v180
	v_exp_f32_e32 v181, v181
	v_add_f32_e32 v62, 1.0, v62
	v_add_f32_e32 v63, 1.0, v63
	v_add_f32_e32 v180, 1.0, v180
	v_add_f32_e32 v181, 1.0, v181
	v_rcp_f32_e32 v62, v62
	v_rcp_f32_e32 v63, v63
	v_rcp_f32_e32 v180, v180
	v_rcp_f32_e32 v181, v181
	v_mul_f32_e32 v62, v62, v178
	v_mul_f32_e32 v63, v63, v162
	v_mul_f32_e32 v180, v180, v179
	v_mul_f32_e32 v181, v181, v166
	v_mul_f32_e32 v62, v62, v180
	v_mul_f32_e32 v63, v63, v181
	v_lshlrev_b32_e32 v178, 16, v163
	v_and_b32_e32 v163, 0xffff0000, v163
	v_lshlrev_b32_e32 v179, 16, v167
	v_and_b32_e32 v167, 0xffff0000, v167
	v_mul_f32_e32 v64, 0xbfb8aa3b, v64
	v_mul_f32_e32 v65, 0xbfb8aa3b, v65
	v_mul_f32_e32 v180, 0xbfb8aa3b, v179
	v_mul_f32_e32 v181, 0xbfb8aa3b, v167
	v_exp_f32_e32 v64, v64
	v_exp_f32_e32 v65, v65
	v_exp_f32_e32 v180, v180
	v_exp_f32_e32 v181, v181
	v_add_f32_e32 v64, 1.0, v64
	v_add_f32_e32 v65, 1.0, v65
	v_add_f32_e32 v180, 1.0, v180
	v_add_f32_e32 v181, 1.0, v181
	v_rcp_f32_e32 v64, v64
	v_rcp_f32_e32 v65, v65
	v_rcp_f32_e32 v180, v180
	v_rcp_f32_e32 v181, v181
	v_mul_f32_e32 v64, v64, v178
	v_mul_f32_e32 v65, v65, v163
	v_mul_f32_e32 v180, v180, v179
	v_mul_f32_e32 v181, v181, v167
	v_mul_f32_e32 v64, v64, v180
	v_mul_f32_e32 v65, v65, v181
	v_lshlrev_b32_e32 v178, 16, v164
	v_and_b32_e32 v164, 0xffff0000, v164
	v_lshlrev_b32_e32 v179, 16, v168
	v_and_b32_e32 v168, 0xffff0000, v168
	v_mul_f32_e32 v58, 0xbfb8aa3b, v58
	v_mul_f32_e32 v59, 0xbfb8aa3b, v59
	v_mul_f32_e32 v180, 0xbfb8aa3b, v179
	v_mul_f32_e32 v181, 0xbfb8aa3b, v168
	v_exp_f32_e32 v58, v58
	v_exp_f32_e32 v59, v59
	v_exp_f32_e32 v180, v180
	v_exp_f32_e32 v181, v181
	v_add_f32_e32 v58, 1.0, v58
	v_add_f32_e32 v59, 1.0, v59
	v_add_f32_e32 v180, 1.0, v180
	v_add_f32_e32 v181, 1.0, v181
	v_rcp_f32_e32 v58, v58
	v_rcp_f32_e32 v59, v59
	v_rcp_f32_e32 v180, v180
	v_rcp_f32_e32 v181, v181
	v_mul_f32_e32 v58, v58, v178
	v_mul_f32_e32 v59, v59, v164
	v_mul_f32_e32 v180, v180, v179
	v_mul_f32_e32 v181, v181, v168
	v_mul_f32_e32 v58, v58, v180
	v_mul_f32_e32 v59, v59, v181
	v_lshlrev_b32_e32 v178, 16, v165
	v_and_b32_e32 v165, 0xffff0000, v165
	v_lshlrev_b32_e32 v179, 16, v169
	v_and_b32_e32 v169, 0xffff0000, v169
	v_mul_f32_e32 v60, 0xbfb8aa3b, v60
	v_mul_f32_e32 v61, 0xbfb8aa3b, v61
	v_mul_f32_e32 v180, 0xbfb8aa3b, v179
	v_mul_f32_e32 v181, 0xbfb8aa3b, v169
	v_exp_f32_e32 v60, v60
	v_exp_f32_e32 v61, v61
	v_exp_f32_e32 v180, v180
	v_exp_f32_e32 v181, v181
	v_add_f32_e32 v60, 1.0, v60
	v_add_f32_e32 v61, 1.0, v61
	v_add_f32_e32 v180, 1.0, v180
	v_add_f32_e32 v181, 1.0, v181
	v_rcp_f32_e32 v60, v60
	v_rcp_f32_e32 v61, v61
	v_rcp_f32_e32 v180, v180
	v_rcp_f32_e32 v181, v181
	v_mul_f32_e32 v60, v60, v178
	v_mul_f32_e32 v61, v61, v165
	v_mul_f32_e32 v180, v180, v179
	v_mul_f32_e32 v181, v181, v169
	v_mul_f32_e32 v60, v60, v180
	v_mul_f32_e32 v61, v61, v181
	v_cvt_pk_bf16_f32 v62, v62, v63
	v_cvt_pk_bf16_f32 v63, v64, v65
	v_cvt_pk_bf16_f32 v64, v58, v59
	v_cvt_pk_bf16_f32 v65, v60, v61
	global_store_dwordx4 v[146:147], v[62:65], off
	global_load_dwordx4 v[162:165], v[142:143], off offset:256
	global_load_dwordx4 v[166:169], v[144:145], off offset:256
	s_waitcnt vmcnt(6)
	v_lshlrev_b32_e32 v178, 16, v170
	v_and_b32_e32 v170, 0xffff0000, v170
	v_lshlrev_b32_e32 v179, 16, v174
	v_and_b32_e32 v174, 0xffff0000, v174
	v_mul_f32_e32 v54, 0xbfb8aa3b, v54
	v_mul_f32_e32 v55, 0xbfb8aa3b, v55
	v_mul_f32_e32 v180, 0xbfb8aa3b, v179
	v_mul_f32_e32 v181, 0xbfb8aa3b, v174
	v_exp_f32_e32 v54, v54
	v_exp_f32_e32 v55, v55
	v_exp_f32_e32 v180, v180
	v_exp_f32_e32 v181, v181
	v_add_f32_e32 v54, 1.0, v54
	v_add_f32_e32 v55, 1.0, v55
	v_add_f32_e32 v180, 1.0, v180
	v_add_f32_e32 v181, 1.0, v181
	v_rcp_f32_e32 v54, v54
	v_rcp_f32_e32 v55, v55
	v_rcp_f32_e32 v180, v180
	v_rcp_f32_e32 v181, v181
	v_mul_f32_e32 v54, v54, v178
	v_mul_f32_e32 v55, v55, v170
	v_mul_f32_e32 v180, v180, v179
	v_mul_f32_e32 v181, v181, v174
	v_mul_f32_e32 v54, v54, v180
	v_mul_f32_e32 v55, v55, v181
	v_lshlrev_b32_e32 v178, 16, v171
	v_and_b32_e32 v171, 0xffff0000, v171
	v_lshlrev_b32_e32 v179, 16, v175
	v_and_b32_e32 v175, 0xffff0000, v175
	v_mul_f32_e32 v56, 0xbfb8aa3b, v56
	v_mul_f32_e32 v57, 0xbfb8aa3b, v57
	v_mul_f32_e32 v180, 0xbfb8aa3b, v179
	v_mul_f32_e32 v181, 0xbfb8aa3b, v175
	v_exp_f32_e32 v56, v56
	v_exp_f32_e32 v57, v57
	v_exp_f32_e32 v180, v180
	v_exp_f32_e32 v181, v181
	v_add_f32_e32 v56, 1.0, v56
	v_add_f32_e32 v57, 1.0, v57
	v_add_f32_e32 v180, 1.0, v180
	v_add_f32_e32 v181, 1.0, v181
	v_rcp_f32_e32 v56, v56
	v_rcp_f32_e32 v57, v57
	v_rcp_f32_e32 v180, v180
	v_rcp_f32_e32 v181, v181
	v_mul_f32_e32 v56, v56, v178
	v_mul_f32_e32 v57, v57, v171
	v_mul_f32_e32 v180, v180, v179
	v_mul_f32_e32 v181, v181, v175
	v_mul_f32_e32 v56, v56, v180
	v_mul_f32_e32 v57, v57, v181
	v_lshlrev_b32_e32 v178, 16, v172
	v_and_b32_e32 v172, 0xffff0000, v172
	v_lshlrev_b32_e32 v179, 16, v176
	v_and_b32_e32 v176, 0xffff0000, v176
	v_mul_f32_e32 v50, 0xbfb8aa3b, v50
	v_mul_f32_e32 v51, 0xbfb8aa3b, v51
	v_mul_f32_e32 v180, 0xbfb8aa3b, v179
	v_mul_f32_e32 v181, 0xbfb8aa3b, v176
	v_exp_f32_e32 v50, v50
	v_exp_f32_e32 v51, v51
	v_exp_f32_e32 v180, v180
	v_exp_f32_e32 v181, v181
	v_add_f32_e32 v50, 1.0, v50
	v_add_f32_e32 v51, 1.0, v51
	v_add_f32_e32 v180, 1.0, v180
	v_add_f32_e32 v181, 1.0, v181
	v_rcp_f32_e32 v50, v50
	v_rcp_f32_e32 v51, v51
	v_rcp_f32_e32 v180, v180
	v_rcp_f32_e32 v181, v181
	v_mul_f32_e32 v50, v50, v178
	v_mul_f32_e32 v51, v51, v172
	v_mul_f32_e32 v180, v180, v179
	v_mul_f32_e32 v181, v181, v176
	v_mul_f32_e32 v50, v50, v180
	v_mul_f32_e32 v51, v51, v181
	v_lshlrev_b32_e32 v178, 16, v173
	v_and_b32_e32 v173, 0xffff0000, v173
	v_lshlrev_b32_e32 v179, 16, v177
	v_and_b32_e32 v177, 0xffff0000, v177
	v_mul_f32_e32 v52, 0xbfb8aa3b, v52
	v_mul_f32_e32 v53, 0xbfb8aa3b, v53
	v_mul_f32_e32 v180, 0xbfb8aa3b, v179
	v_mul_f32_e32 v181, 0xbfb8aa3b, v177
	v_exp_f32_e32 v52, v52
	v_exp_f32_e32 v53, v53
	v_exp_f32_e32 v180, v180
	v_exp_f32_e32 v181, v181
	v_add_f32_e32 v52, 1.0, v52
	v_add_f32_e32 v53, 1.0, v53
	v_add_f32_e32 v180, 1.0, v180
	v_add_f32_e32 v181, 1.0, v181
	v_rcp_f32_e32 v52, v52
	v_rcp_f32_e32 v53, v53
	v_rcp_f32_e32 v180, v180
	v_rcp_f32_e32 v181, v181
	v_mul_f32_e32 v52, v52, v178
	v_mul_f32_e32 v53, v53, v173
	v_mul_f32_e32 v180, v180, v179
	v_mul_f32_e32 v181, v181, v177
	v_mul_f32_e32 v52, v52, v180
	v_mul_f32_e32 v53, v53, v181
	v_cvt_pk_bf16_f32 v54, v54, v55
	v_cvt_pk_bf16_f32 v55, v56, v57
	v_cvt_pk_bf16_f32 v56, v50, v51
	v_cvt_pk_bf16_f32 v57, v52, v53
	global_store_dwordx4 v[146:147], v[54:57], off offset:256
	s_mov_b64 s[58:59], 0x20000
	v_lshl_add_u64 v[146:147], v[146:147], 0, s[58:59]
	s_mov_b64 s[58:59], 0x8000
	v_lshl_add_u64 v[142:143], v[142:143], 0, s[58:59]
	s_mov_b64 s[58:59], 0x4000
	v_lshl_add_u64 v[144:145], v[144:145], 0, s[58:59]
	global_load_dwordx4 v[170:173], v[142:143], off
	global_load_dwordx4 v[174:177], v[144:145], off
	s_waitcnt vmcnt(6)
	v_lshlrev_b32_e32 v178, 16, v154
	v_and_b32_e32 v154, 0xffff0000, v154
	v_lshlrev_b32_e32 v179, 16, v158
	v_and_b32_e32 v158, 0xffff0000, v158
	v_mul_f32_e32 v46, 0xbfb8aa3b, v46
	v_mul_f32_e32 v47, 0xbfb8aa3b, v47
	v_mul_f32_e32 v180, 0xbfb8aa3b, v179
	v_mul_f32_e32 v181, 0xbfb8aa3b, v158
	v_exp_f32_e32 v46, v46
	v_exp_f32_e32 v47, v47
	v_exp_f32_e32 v180, v180
	v_exp_f32_e32 v181, v181
	v_add_f32_e32 v46, 1.0, v46
	v_add_f32_e32 v47, 1.0, v47
	v_add_f32_e32 v180, 1.0, v180
	v_add_f32_e32 v181, 1.0, v181
	v_rcp_f32_e32 v46, v46
	v_rcp_f32_e32 v47, v47
	v_rcp_f32_e32 v180, v180
	v_rcp_f32_e32 v181, v181
	v_mul_f32_e32 v46, v46, v178
	v_mul_f32_e32 v47, v47, v154
	v_mul_f32_e32 v180, v180, v179
	v_mul_f32_e32 v181, v181, v158
	v_mul_f32_e32 v46, v46, v180
	v_mul_f32_e32 v47, v47, v181
	v_lshlrev_b32_e32 v178, 16, v155
	v_and_b32_e32 v155, 0xffff0000, v155
	v_lshlrev_b32_e32 v179, 16, v159
	v_and_b32_e32 v159, 0xffff0000, v159
	v_mul_f32_e32 v48, 0xbfb8aa3b, v48
	v_mul_f32_e32 v49, 0xbfb8aa3b, v49
	v_mul_f32_e32 v180, 0xbfb8aa3b, v179
	v_mul_f32_e32 v181, 0xbfb8aa3b, v159
	v_exp_f32_e32 v48, v48
	v_exp_f32_e32 v49, v49
	v_exp_f32_e32 v180, v180
	v_exp_f32_e32 v181, v181
	v_add_f32_e32 v48, 1.0, v48
	v_add_f32_e32 v49, 1.0, v49
	v_add_f32_e32 v180, 1.0, v180
	v_add_f32_e32 v181, 1.0, v181
	v_rcp_f32_e32 v48, v48
	v_rcp_f32_e32 v49, v49
	v_rcp_f32_e32 v180, v180
	v_rcp_f32_e32 v181, v181
	v_mul_f32_e32 v48, v48, v178
	v_mul_f32_e32 v49, v49, v155
	v_mul_f32_e32 v180, v180, v179
	v_mul_f32_e32 v181, v181, v159
	v_mul_f32_e32 v48, v48, v180
	v_mul_f32_e32 v49, v49, v181
	v_lshlrev_b32_e32 v178, 16, v156
	v_and_b32_e32 v156, 0xffff0000, v156
	v_lshlrev_b32_e32 v179, 16, v160
	v_and_b32_e32 v160, 0xffff0000, v160
	v_mul_f32_e32 v42, 0xbfb8aa3b, v42
	v_mul_f32_e32 v43, 0xbfb8aa3b, v43
	v_mul_f32_e32 v180, 0xbfb8aa3b, v179
	v_mul_f32_e32 v181, 0xbfb8aa3b, v160
	v_exp_f32_e32 v42, v42
	v_exp_f32_e32 v43, v43
	v_exp_f32_e32 v180, v180
	v_exp_f32_e32 v181, v181
	v_add_f32_e32 v42, 1.0, v42
	v_add_f32_e32 v43, 1.0, v43
	v_add_f32_e32 v180, 1.0, v180
	v_add_f32_e32 v181, 1.0, v181
	v_rcp_f32_e32 v42, v42
	v_rcp_f32_e32 v43, v43
	v_rcp_f32_e32 v180, v180
	v_rcp_f32_e32 v181, v181
	v_mul_f32_e32 v42, v42, v178
	v_mul_f32_e32 v43, v43, v156
	v_mul_f32_e32 v180, v180, v179
	v_mul_f32_e32 v181, v181, v160
	v_mul_f32_e32 v42, v42, v180
	v_mul_f32_e32 v43, v43, v181
	v_lshlrev_b32_e32 v178, 16, v157
	v_and_b32_e32 v157, 0xffff0000, v157
	v_lshlrev_b32_e32 v179, 16, v161
	v_and_b32_e32 v161, 0xffff0000, v161
	v_mul_f32_e32 v44, 0xbfb8aa3b, v44
	v_mul_f32_e32 v45, 0xbfb8aa3b, v45
	v_mul_f32_e32 v180, 0xbfb8aa3b, v179
	v_mul_f32_e32 v181, 0xbfb8aa3b, v161
	v_exp_f32_e32 v44, v44
	v_exp_f32_e32 v45, v45
	v_exp_f32_e32 v180, v180
	v_exp_f32_e32 v181, v181
	v_add_f32_e32 v44, 1.0, v44
	v_add_f32_e32 v45, 1.0, v45
	v_add_f32_e32 v180, 1.0, v180
	v_add_f32_e32 v181, 1.0, v181
	v_rcp_f32_e32 v44, v44
	v_rcp_f32_e32 v45, v45
	v_rcp_f32_e32 v180, v180
	v_rcp_f32_e32 v181, v181
	v_mul_f32_e32 v44, v44, v178
	v_mul_f32_e32 v45, v45, v157
	v_mul_f32_e32 v180, v180, v179
	v_mul_f32_e32 v181, v181, v161
	v_mul_f32_e32 v44, v44, v180
	v_mul_f32_e32 v45, v45, v181
	v_cvt_pk_bf16_f32 v46, v46, v47
	v_cvt_pk_bf16_f32 v47, v48, v49
	v_cvt_pk_bf16_f32 v48, v42, v43
	v_cvt_pk_bf16_f32 v49, v44, v45
	global_store_dwordx4 v[146:147], v[46:49], off
	global_load_dwordx4 v[154:157], v[142:143], off offset:256
	global_load_dwordx4 v[158:161], v[144:145], off offset:256
	s_waitcnt vmcnt(6)
	v_lshlrev_b32_e32 v178, 16, v162
	v_and_b32_e32 v162, 0xffff0000, v162
	v_lshlrev_b32_e32 v179, 16, v166
	v_and_b32_e32 v166, 0xffff0000, v166
	v_mul_f32_e32 v38, 0xbfb8aa3b, v38
	v_mul_f32_e32 v39, 0xbfb8aa3b, v39
	v_mul_f32_e32 v180, 0xbfb8aa3b, v179
	v_mul_f32_e32 v181, 0xbfb8aa3b, v166
	v_exp_f32_e32 v38, v38
	v_exp_f32_e32 v39, v39
	v_exp_f32_e32 v180, v180
	v_exp_f32_e32 v181, v181
	v_add_f32_e32 v38, 1.0, v38
	v_add_f32_e32 v39, 1.0, v39
	v_add_f32_e32 v180, 1.0, v180
	v_add_f32_e32 v181, 1.0, v181
	v_rcp_f32_e32 v38, v38
	v_rcp_f32_e32 v39, v39
	v_rcp_f32_e32 v180, v180
	v_rcp_f32_e32 v181, v181
	v_mul_f32_e32 v38, v38, v178
	v_mul_f32_e32 v39, v39, v162
	v_mul_f32_e32 v180, v180, v179
	v_mul_f32_e32 v181, v181, v166
	v_mul_f32_e32 v38, v38, v180
	v_mul_f32_e32 v39, v39, v181
	v_lshlrev_b32_e32 v178, 16, v163
	v_and_b32_e32 v163, 0xffff0000, v163
	v_lshlrev_b32_e32 v179, 16, v167
	v_and_b32_e32 v167, 0xffff0000, v167
	v_mul_f32_e32 v40, 0xbfb8aa3b, v40
	v_mul_f32_e32 v41, 0xbfb8aa3b, v41
	v_mul_f32_e32 v180, 0xbfb8aa3b, v179
	v_mul_f32_e32 v181, 0xbfb8aa3b, v167
	v_exp_f32_e32 v40, v40
	v_exp_f32_e32 v41, v41
	v_exp_f32_e32 v180, v180
	v_exp_f32_e32 v181, v181
	v_add_f32_e32 v40, 1.0, v40
	v_add_f32_e32 v41, 1.0, v41
	v_add_f32_e32 v180, 1.0, v180
	v_add_f32_e32 v181, 1.0, v181
	v_rcp_f32_e32 v40, v40
	v_rcp_f32_e32 v41, v41
	v_rcp_f32_e32 v180, v180
	v_rcp_f32_e32 v181, v181
	v_mul_f32_e32 v40, v40, v178
	v_mul_f32_e32 v41, v41, v163
	v_mul_f32_e32 v180, v180, v179
	v_mul_f32_e32 v181, v181, v167
	v_mul_f32_e32 v40, v40, v180
	v_mul_f32_e32 v41, v41, v181
	v_lshlrev_b32_e32 v178, 16, v164
	v_and_b32_e32 v164, 0xffff0000, v164
	v_lshlrev_b32_e32 v179, 16, v168
	v_and_b32_e32 v168, 0xffff0000, v168
	v_mul_f32_e32 v34, 0xbfb8aa3b, v34
	v_mul_f32_e32 v35, 0xbfb8aa3b, v35
	v_mul_f32_e32 v180, 0xbfb8aa3b, v179
	v_mul_f32_e32 v181, 0xbfb8aa3b, v168
	v_exp_f32_e32 v34, v34
	v_exp_f32_e32 v35, v35
	v_exp_f32_e32 v180, v180
	v_exp_f32_e32 v181, v181
	v_add_f32_e32 v34, 1.0, v34
	v_add_f32_e32 v35, 1.0, v35
	v_add_f32_e32 v180, 1.0, v180
	v_add_f32_e32 v181, 1.0, v181
	v_rcp_f32_e32 v34, v34
	v_rcp_f32_e32 v35, v35
	v_rcp_f32_e32 v180, v180
	v_rcp_f32_e32 v181, v181
	v_mul_f32_e32 v34, v34, v178
	v_mul_f32_e32 v35, v35, v164
	v_mul_f32_e32 v180, v180, v179
	v_mul_f32_e32 v181, v181, v168
	v_mul_f32_e32 v34, v34, v180
	v_mul_f32_e32 v35, v35, v181
	v_lshlrev_b32_e32 v178, 16, v165
	v_and_b32_e32 v165, 0xffff0000, v165
	v_lshlrev_b32_e32 v179, 16, v169
	v_and_b32_e32 v169, 0xffff0000, v169
	v_mul_f32_e32 v36, 0xbfb8aa3b, v36
	v_mul_f32_e32 v37, 0xbfb8aa3b, v37
	v_mul_f32_e32 v180, 0xbfb8aa3b, v179
	v_mul_f32_e32 v181, 0xbfb8aa3b, v169
	v_exp_f32_e32 v36, v36
	v_exp_f32_e32 v37, v37
	v_exp_f32_e32 v180, v180
	v_exp_f32_e32 v181, v181
	v_add_f32_e32 v36, 1.0, v36
	v_add_f32_e32 v37, 1.0, v37
	v_add_f32_e32 v180, 1.0, v180
	v_add_f32_e32 v181, 1.0, v181
	v_rcp_f32_e32 v36, v36
	v_rcp_f32_e32 v37, v37
	v_rcp_f32_e32 v180, v180
	v_rcp_f32_e32 v181, v181
	v_mul_f32_e32 v36, v36, v178
	v_mul_f32_e32 v37, v37, v165
	v_mul_f32_e32 v180, v180, v179
	v_mul_f32_e32 v181, v181, v169
	v_mul_f32_e32 v36, v36, v180
	v_mul_f32_e32 v37, v37, v181
	v_cvt_pk_bf16_f32 v38, v38, v39
	v_cvt_pk_bf16_f32 v39, v40, v41
	v_cvt_pk_bf16_f32 v40, v34, v35
	v_cvt_pk_bf16_f32 v41, v36, v37
	global_store_dwordx4 v[146:147], v[38:41], off offset:256
	s_mov_b64 s[58:59], 0x20000
	v_lshl_add_u64 v[146:147], v[146:147], 0, s[58:59]
	s_mov_b64 s[58:59], 0x8000
	v_lshl_add_u64 v[142:143], v[142:143], 0, s[58:59]
	s_mov_b64 s[58:59], 0x4000
	v_lshl_add_u64 v[144:145], v[144:145], 0, s[58:59]
	global_load_dwordx4 v[162:165], v[142:143], off
	global_load_dwordx4 v[166:169], v[144:145], off
	s_waitcnt vmcnt(6)
	v_lshlrev_b32_e32 v178, 16, v170
	v_and_b32_e32 v170, 0xffff0000, v170
	v_lshlrev_b32_e32 v179, 16, v174
	v_and_b32_e32 v174, 0xffff0000, v174
	v_mul_f32_e32 v30, 0xbfb8aa3b, v30
	v_mul_f32_e32 v31, 0xbfb8aa3b, v31
	v_mul_f32_e32 v180, 0xbfb8aa3b, v179
	v_mul_f32_e32 v181, 0xbfb8aa3b, v174
	v_exp_f32_e32 v30, v30
	v_exp_f32_e32 v31, v31
	v_exp_f32_e32 v180, v180
	v_exp_f32_e32 v181, v181
	v_add_f32_e32 v30, 1.0, v30
	v_add_f32_e32 v31, 1.0, v31
	v_add_f32_e32 v180, 1.0, v180
	v_add_f32_e32 v181, 1.0, v181
	v_rcp_f32_e32 v30, v30
	v_rcp_f32_e32 v31, v31
	v_rcp_f32_e32 v180, v180
	v_rcp_f32_e32 v181, v181
	v_mul_f32_e32 v30, v30, v178
	v_mul_f32_e32 v31, v31, v170
	v_mul_f32_e32 v180, v180, v179
	v_mul_f32_e32 v181, v181, v174
	v_mul_f32_e32 v30, v30, v180
	v_mul_f32_e32 v31, v31, v181
	v_lshlrev_b32_e32 v178, 16, v171
	v_and_b32_e32 v171, 0xffff0000, v171
	v_lshlrev_b32_e32 v179, 16, v175
	v_and_b32_e32 v175, 0xffff0000, v175
	v_mul_f32_e32 v32, 0xbfb8aa3b, v32
	v_mul_f32_e32 v33, 0xbfb8aa3b, v33
	v_mul_f32_e32 v180, 0xbfb8aa3b, v179
	v_mul_f32_e32 v181, 0xbfb8aa3b, v175
	v_exp_f32_e32 v32, v32
	v_exp_f32_e32 v33, v33
	v_exp_f32_e32 v180, v180
	v_exp_f32_e32 v181, v181
	v_add_f32_e32 v32, 1.0, v32
	v_add_f32_e32 v33, 1.0, v33
	v_add_f32_e32 v180, 1.0, v180
	v_add_f32_e32 v181, 1.0, v181
	v_rcp_f32_e32 v32, v32
	v_rcp_f32_e32 v33, v33
	v_rcp_f32_e32 v180, v180
	v_rcp_f32_e32 v181, v181
	v_mul_f32_e32 v32, v32, v178
	v_mul_f32_e32 v33, v33, v171
	v_mul_f32_e32 v180, v180, v179
	v_mul_f32_e32 v181, v181, v175
	v_mul_f32_e32 v32, v32, v180
	v_mul_f32_e32 v33, v33, v181
	v_lshlrev_b32_e32 v178, 16, v172
	v_and_b32_e32 v172, 0xffff0000, v172
	v_lshlrev_b32_e32 v179, 16, v176
	v_and_b32_e32 v176, 0xffff0000, v176
	v_mul_f32_e32 v26, 0xbfb8aa3b, v26
	v_mul_f32_e32 v27, 0xbfb8aa3b, v27
	v_mul_f32_e32 v180, 0xbfb8aa3b, v179
	v_mul_f32_e32 v181, 0xbfb8aa3b, v176
	v_exp_f32_e32 v26, v26
	v_exp_f32_e32 v27, v27
	v_exp_f32_e32 v180, v180
	v_exp_f32_e32 v181, v181
	v_add_f32_e32 v26, 1.0, v26
	v_add_f32_e32 v27, 1.0, v27
	v_add_f32_e32 v180, 1.0, v180
	v_add_f32_e32 v181, 1.0, v181
	v_rcp_f32_e32 v26, v26
	v_rcp_f32_e32 v27, v27
	v_rcp_f32_e32 v180, v180
	v_rcp_f32_e32 v181, v181
	v_mul_f32_e32 v26, v26, v178
	v_mul_f32_e32 v27, v27, v172
	v_mul_f32_e32 v180, v180, v179
	v_mul_f32_e32 v181, v181, v176
	v_mul_f32_e32 v26, v26, v180
	v_mul_f32_e32 v27, v27, v181
	v_lshlrev_b32_e32 v178, 16, v173
	v_and_b32_e32 v173, 0xffff0000, v173
	v_lshlrev_b32_e32 v179, 16, v177
	v_and_b32_e32 v177, 0xffff0000, v177
	v_mul_f32_e32 v28, 0xbfb8aa3b, v28
	v_mul_f32_e32 v29, 0xbfb8aa3b, v29
	v_mul_f32_e32 v180, 0xbfb8aa3b, v179
	v_mul_f32_e32 v181, 0xbfb8aa3b, v177
	v_exp_f32_e32 v28, v28
	v_exp_f32_e32 v29, v29
	v_exp_f32_e32 v180, v180
	v_exp_f32_e32 v181, v181
	v_add_f32_e32 v28, 1.0, v28
	v_add_f32_e32 v29, 1.0, v29
	v_add_f32_e32 v180, 1.0, v180
	v_add_f32_e32 v181, 1.0, v181
	v_rcp_f32_e32 v28, v28
	v_rcp_f32_e32 v29, v29
	v_rcp_f32_e32 v180, v180
	v_rcp_f32_e32 v181, v181
	v_mul_f32_e32 v28, v28, v178
	v_mul_f32_e32 v29, v29, v173
	v_mul_f32_e32 v180, v180, v179
	v_mul_f32_e32 v181, v181, v177
	v_mul_f32_e32 v28, v28, v180
	v_mul_f32_e32 v29, v29, v181
	v_cvt_pk_bf16_f32 v30, v30, v31
	v_cvt_pk_bf16_f32 v31, v32, v33
	v_cvt_pk_bf16_f32 v32, v26, v27
	v_cvt_pk_bf16_f32 v33, v28, v29
	global_store_dwordx4 v[146:147], v[30:33], off
	global_load_dwordx4 v[170:173], v[142:143], off offset:256
	global_load_dwordx4 v[174:177], v[144:145], off offset:256
	s_waitcnt vmcnt(6)
	v_lshlrev_b32_e32 v178, 16, v154
	v_and_b32_e32 v154, 0xffff0000, v154
	v_lshlrev_b32_e32 v179, 16, v158
	v_and_b32_e32 v158, 0xffff0000, v158
	v_mul_f32_e32 v22, 0xbfb8aa3b, v22
	v_mul_f32_e32 v23, 0xbfb8aa3b, v23
	v_mul_f32_e32 v180, 0xbfb8aa3b, v179
	v_mul_f32_e32 v181, 0xbfb8aa3b, v158
	v_exp_f32_e32 v22, v22
	v_exp_f32_e32 v23, v23
	v_exp_f32_e32 v180, v180
	v_exp_f32_e32 v181, v181
	v_add_f32_e32 v22, 1.0, v22
	v_add_f32_e32 v23, 1.0, v23
	v_add_f32_e32 v180, 1.0, v180
	v_add_f32_e32 v181, 1.0, v181
	v_rcp_f32_e32 v22, v22
	v_rcp_f32_e32 v23, v23
	v_rcp_f32_e32 v180, v180
	v_rcp_f32_e32 v181, v181
	v_mul_f32_e32 v22, v22, v178
	v_mul_f32_e32 v23, v23, v154
	v_mul_f32_e32 v180, v180, v179
	v_mul_f32_e32 v181, v181, v158
	v_mul_f32_e32 v22, v22, v180
	v_mul_f32_e32 v23, v23, v181
	v_lshlrev_b32_e32 v178, 16, v155
	v_and_b32_e32 v155, 0xffff0000, v155
	v_lshlrev_b32_e32 v179, 16, v159
	v_and_b32_e32 v159, 0xffff0000, v159
	v_mul_f32_e32 v24, 0xbfb8aa3b, v24
	v_mul_f32_e32 v25, 0xbfb8aa3b, v25
	v_mul_f32_e32 v180, 0xbfb8aa3b, v179
	v_mul_f32_e32 v181, 0xbfb8aa3b, v159
	v_exp_f32_e32 v24, v24
	v_exp_f32_e32 v25, v25
	v_exp_f32_e32 v180, v180
	v_exp_f32_e32 v181, v181
	v_add_f32_e32 v24, 1.0, v24
	v_add_f32_e32 v25, 1.0, v25
	v_add_f32_e32 v180, 1.0, v180
	v_add_f32_e32 v181, 1.0, v181
	v_rcp_f32_e32 v24, v24
	v_rcp_f32_e32 v25, v25
	v_rcp_f32_e32 v180, v180
	v_rcp_f32_e32 v181, v181
	v_mul_f32_e32 v24, v24, v178
	v_mul_f32_e32 v25, v25, v155
	v_mul_f32_e32 v180, v180, v179
	v_mul_f32_e32 v181, v181, v159
	v_mul_f32_e32 v24, v24, v180
	v_mul_f32_e32 v25, v25, v181
	v_lshlrev_b32_e32 v178, 16, v156
	v_and_b32_e32 v156, 0xffff0000, v156
	v_lshlrev_b32_e32 v179, 16, v160
	v_and_b32_e32 v160, 0xffff0000, v160
	v_mul_f32_e32 v18, 0xbfb8aa3b, v18
	v_mul_f32_e32 v19, 0xbfb8aa3b, v19
	v_mul_f32_e32 v180, 0xbfb8aa3b, v179
	v_mul_f32_e32 v181, 0xbfb8aa3b, v160
	v_exp_f32_e32 v18, v18
	v_exp_f32_e32 v19, v19
	v_exp_f32_e32 v180, v180
	v_exp_f32_e32 v181, v181
	v_add_f32_e32 v18, 1.0, v18
	v_add_f32_e32 v19, 1.0, v19
	v_add_f32_e32 v180, 1.0, v180
	v_add_f32_e32 v181, 1.0, v181
	v_rcp_f32_e32 v18, v18
	v_rcp_f32_e32 v19, v19
	v_rcp_f32_e32 v180, v180
	v_rcp_f32_e32 v181, v181
	v_mul_f32_e32 v18, v18, v178
	v_mul_f32_e32 v19, v19, v156
	v_mul_f32_e32 v180, v180, v179
	v_mul_f32_e32 v181, v181, v160
	v_mul_f32_e32 v18, v18, v180
	v_mul_f32_e32 v19, v19, v181
	v_lshlrev_b32_e32 v178, 16, v157
	v_and_b32_e32 v157, 0xffff0000, v157
	v_lshlrev_b32_e32 v179, 16, v161
	v_and_b32_e32 v161, 0xffff0000, v161
	v_mul_f32_e32 v20, 0xbfb8aa3b, v20
	v_mul_f32_e32 v21, 0xbfb8aa3b, v21
	v_mul_f32_e32 v180, 0xbfb8aa3b, v179
	v_mul_f32_e32 v181, 0xbfb8aa3b, v161
	v_exp_f32_e32 v20, v20
	v_exp_f32_e32 v21, v21
	v_exp_f32_e32 v180, v180
	v_exp_f32_e32 v181, v181
	v_add_f32_e32 v20, 1.0, v20
	v_add_f32_e32 v21, 1.0, v21
	v_add_f32_e32 v180, 1.0, v180
	v_add_f32_e32 v181, 1.0, v181
	v_rcp_f32_e32 v20, v20
	v_rcp_f32_e32 v21, v21
	v_rcp_f32_e32 v180, v180
	v_rcp_f32_e32 v181, v181
	v_mul_f32_e32 v20, v20, v178
	v_mul_f32_e32 v21, v21, v157
	v_mul_f32_e32 v180, v180, v179
	v_mul_f32_e32 v181, v181, v161
	v_mul_f32_e32 v20, v20, v180
	v_mul_f32_e32 v21, v21, v181
	v_cvt_pk_bf16_f32 v22, v22, v23
	v_cvt_pk_bf16_f32 v23, v24, v25
	v_cvt_pk_bf16_f32 v24, v18, v19
	v_cvt_pk_bf16_f32 v25, v20, v21
	global_store_dwordx4 v[146:147], v[22:25], off offset:256
	s_mov_b64 s[58:59], 0x20000
	v_lshl_add_u64 v[146:147], v[146:147], 0, s[58:59]
	s_waitcnt vmcnt(4)
	v_lshlrev_b32_e32 v178, 16, v162
	v_and_b32_e32 v162, 0xffff0000, v162
	v_lshlrev_b32_e32 v179, 16, v166
	v_and_b32_e32 v166, 0xffff0000, v166
	v_mul_f32_e32 v14, 0xbfb8aa3b, v14
	v_mul_f32_e32 v15, 0xbfb8aa3b, v15
	v_mul_f32_e32 v180, 0xbfb8aa3b, v179
	v_mul_f32_e32 v181, 0xbfb8aa3b, v166
	v_exp_f32_e32 v14, v14
	v_exp_f32_e32 v15, v15
	v_exp_f32_e32 v180, v180
	v_exp_f32_e32 v181, v181
	v_add_f32_e32 v14, 1.0, v14
	v_add_f32_e32 v15, 1.0, v15
	v_add_f32_e32 v180, 1.0, v180
	v_add_f32_e32 v181, 1.0, v181
	v_rcp_f32_e32 v14, v14
	v_rcp_f32_e32 v15, v15
	v_rcp_f32_e32 v180, v180
	v_rcp_f32_e32 v181, v181
	v_mul_f32_e32 v14, v14, v178
	v_mul_f32_e32 v15, v15, v162
	v_mul_f32_e32 v180, v180, v179
	v_mul_f32_e32 v181, v181, v166
	v_mul_f32_e32 v14, v14, v180
	v_mul_f32_e32 v15, v15, v181
	v_lshlrev_b32_e32 v178, 16, v163
	v_and_b32_e32 v163, 0xffff0000, v163
	v_lshlrev_b32_e32 v179, 16, v167
	v_and_b32_e32 v167, 0xffff0000, v167
	v_mul_f32_e32 v16, 0xbfb8aa3b, v16
	v_mul_f32_e32 v17, 0xbfb8aa3b, v17
	v_mul_f32_e32 v180, 0xbfb8aa3b, v179
	v_mul_f32_e32 v181, 0xbfb8aa3b, v167
	v_exp_f32_e32 v16, v16
	v_exp_f32_e32 v17, v17
	v_exp_f32_e32 v180, v180
	v_exp_f32_e32 v181, v181
	v_add_f32_e32 v16, 1.0, v16
	v_add_f32_e32 v17, 1.0, v17
	v_add_f32_e32 v180, 1.0, v180
	v_add_f32_e32 v181, 1.0, v181
	v_rcp_f32_e32 v16, v16
	v_rcp_f32_e32 v17, v17
	v_rcp_f32_e32 v180, v180
	v_rcp_f32_e32 v181, v181
	v_mul_f32_e32 v16, v16, v178
	v_mul_f32_e32 v17, v17, v163
	v_mul_f32_e32 v180, v180, v179
	v_mul_f32_e32 v181, v181, v167
	v_mul_f32_e32 v16, v16, v180
	v_mul_f32_e32 v17, v17, v181
	v_lshlrev_b32_e32 v178, 16, v164
	v_and_b32_e32 v164, 0xffff0000, v164
	v_lshlrev_b32_e32 v179, 16, v168
	v_and_b32_e32 v168, 0xffff0000, v168
	v_mul_f32_e32 v10, 0xbfb8aa3b, v10
	v_mul_f32_e32 v11, 0xbfb8aa3b, v11
	v_mul_f32_e32 v180, 0xbfb8aa3b, v179
	v_mul_f32_e32 v181, 0xbfb8aa3b, v168
	v_exp_f32_e32 v10, v10
	v_exp_f32_e32 v11, v11
	v_exp_f32_e32 v180, v180
	v_exp_f32_e32 v181, v181
	v_add_f32_e32 v10, 1.0, v10
	v_add_f32_e32 v11, 1.0, v11
	v_add_f32_e32 v180, 1.0, v180
	v_add_f32_e32 v181, 1.0, v181
	v_rcp_f32_e32 v10, v10
	v_rcp_f32_e32 v11, v11
	v_rcp_f32_e32 v180, v180
	v_rcp_f32_e32 v181, v181
	v_mul_f32_e32 v10, v10, v178
	v_mul_f32_e32 v11, v11, v164
	v_mul_f32_e32 v180, v180, v179
	v_mul_f32_e32 v181, v181, v168
	v_mul_f32_e32 v10, v10, v180
	v_mul_f32_e32 v11, v11, v181
	v_lshlrev_b32_e32 v178, 16, v165
	v_and_b32_e32 v165, 0xffff0000, v165
	v_lshlrev_b32_e32 v179, 16, v169
	v_and_b32_e32 v169, 0xffff0000, v169
	v_mul_f32_e32 v12, 0xbfb8aa3b, v12
	v_mul_f32_e32 v13, 0xbfb8aa3b, v13
	v_mul_f32_e32 v180, 0xbfb8aa3b, v179
	v_mul_f32_e32 v181, 0xbfb8aa3b, v169
	v_exp_f32_e32 v12, v12
	v_exp_f32_e32 v13, v13
	v_exp_f32_e32 v180, v180
	v_exp_f32_e32 v181, v181
	v_add_f32_e32 v12, 1.0, v12
	v_add_f32_e32 v13, 1.0, v13
	v_add_f32_e32 v180, 1.0, v180
	v_add_f32_e32 v181, 1.0, v181
	v_rcp_f32_e32 v12, v12
	v_rcp_f32_e32 v13, v13
	v_rcp_f32_e32 v180, v180
	v_rcp_f32_e32 v181, v181
	v_mul_f32_e32 v12, v12, v178
	v_mul_f32_e32 v13, v13, v165
	v_mul_f32_e32 v180, v180, v179
	v_mul_f32_e32 v181, v181, v169
	v_mul_f32_e32 v12, v12, v180
	v_mul_f32_e32 v13, v13, v181
	v_cvt_pk_bf16_f32 v14, v14, v15
	v_cvt_pk_bf16_f32 v15, v16, v17
	v_cvt_pk_bf16_f32 v16, v10, v11
	v_cvt_pk_bf16_f32 v17, v12, v13
	global_store_dwordx4 v[146:147], v[14:17], off
	s_waitcnt vmcnt(2)
	v_lshlrev_b32_e32 v178, 16, v170
	v_and_b32_e32 v170, 0xffff0000, v170
	v_lshlrev_b32_e32 v179, 16, v174
	v_and_b32_e32 v174, 0xffff0000, v174
	v_mul_f32_e32 v6, 0xbfb8aa3b, v6
	v_mul_f32_e32 v7, 0xbfb8aa3b, v7
	v_mul_f32_e32 v180, 0xbfb8aa3b, v179
	v_mul_f32_e32 v181, 0xbfb8aa3b, v174
	v_exp_f32_e32 v6, v6
	v_exp_f32_e32 v7, v7
	v_exp_f32_e32 v180, v180
	v_exp_f32_e32 v181, v181
	v_add_f32_e32 v6, 1.0, v6
	v_add_f32_e32 v7, 1.0, v7
	v_add_f32_e32 v180, 1.0, v180
	v_add_f32_e32 v181, 1.0, v181
	v_rcp_f32_e32 v6, v6
	v_rcp_f32_e32 v7, v7
	v_rcp_f32_e32 v180, v180
	v_rcp_f32_e32 v181, v181
	v_mul_f32_e32 v6, v6, v178
	v_mul_f32_e32 v7, v7, v170
	v_mul_f32_e32 v180, v180, v179
	v_mul_f32_e32 v181, v181, v174
	v_mul_f32_e32 v6, v6, v180
	v_mul_f32_e32 v7, v7, v181
	v_lshlrev_b32_e32 v178, 16, v171
	v_and_b32_e32 v171, 0xffff0000, v171
	v_lshlrev_b32_e32 v179, 16, v175
	v_and_b32_e32 v175, 0xffff0000, v175
	v_mul_f32_e32 v8, 0xbfb8aa3b, v8
	v_mul_f32_e32 v9, 0xbfb8aa3b, v9
	v_mul_f32_e32 v180, 0xbfb8aa3b, v179
	v_mul_f32_e32 v181, 0xbfb8aa3b, v175
	v_exp_f32_e32 v8, v8
	v_exp_f32_e32 v9, v9
	v_exp_f32_e32 v180, v180
	v_exp_f32_e32 v181, v181
	v_add_f32_e32 v8, 1.0, v8
	v_add_f32_e32 v9, 1.0, v9
	v_add_f32_e32 v180, 1.0, v180
	v_add_f32_e32 v181, 1.0, v181
	v_rcp_f32_e32 v8, v8
	v_rcp_f32_e32 v9, v9
	v_rcp_f32_e32 v180, v180
	v_rcp_f32_e32 v181, v181
	v_mul_f32_e32 v8, v8, v178
	v_mul_f32_e32 v9, v9, v171
	v_mul_f32_e32 v180, v180, v179
	v_mul_f32_e32 v181, v181, v175
	v_mul_f32_e32 v8, v8, v180
	v_mul_f32_e32 v9, v9, v181
	v_lshlrev_b32_e32 v178, 16, v172
	v_and_b32_e32 v172, 0xffff0000, v172
	v_lshlrev_b32_e32 v179, 16, v176
	v_and_b32_e32 v176, 0xffff0000, v176
	v_mul_f32_e32 v2, 0xbfb8aa3b, v2
	v_mul_f32_e32 v3, 0xbfb8aa3b, v3
	v_mul_f32_e32 v180, 0xbfb8aa3b, v179
	v_mul_f32_e32 v181, 0xbfb8aa3b, v176
	v_exp_f32_e32 v2, v2
	v_exp_f32_e32 v3, v3
	v_exp_f32_e32 v180, v180
	v_exp_f32_e32 v181, v181
	v_add_f32_e32 v2, 1.0, v2
	v_add_f32_e32 v3, 1.0, v3
	v_add_f32_e32 v180, 1.0, v180
	v_add_f32_e32 v181, 1.0, v181
	v_rcp_f32_e32 v2, v2
	v_rcp_f32_e32 v3, v3
	v_rcp_f32_e32 v180, v180
	v_rcp_f32_e32 v181, v181
	v_mul_f32_e32 v2, v2, v178
	v_mul_f32_e32 v3, v3, v172
	v_mul_f32_e32 v180, v180, v179
	v_mul_f32_e32 v181, v181, v176
	v_mul_f32_e32 v2, v2, v180
	v_mul_f32_e32 v3, v3, v181
	v_lshlrev_b32_e32 v178, 16, v173
	v_and_b32_e32 v173, 0xffff0000, v173
	v_lshlrev_b32_e32 v179, 16, v177
	v_and_b32_e32 v177, 0xffff0000, v177
	v_mul_f32_e32 v4, 0xbfb8aa3b, v4
	v_mul_f32_e32 v5, 0xbfb8aa3b, v5
	v_mul_f32_e32 v180, 0xbfb8aa3b, v179
	v_mul_f32_e32 v181, 0xbfb8aa3b, v177
	v_exp_f32_e32 v4, v4
	v_exp_f32_e32 v5, v5
	v_exp_f32_e32 v180, v180
	v_exp_f32_e32 v181, v181
	v_add_f32_e32 v4, 1.0, v4
	v_add_f32_e32 v5, 1.0, v5
	v_add_f32_e32 v180, 1.0, v180
	v_add_f32_e32 v181, 1.0, v181
	v_rcp_f32_e32 v4, v4
	v_rcp_f32_e32 v5, v5
	v_rcp_f32_e32 v180, v180
	v_rcp_f32_e32 v181, v181
	v_mul_f32_e32 v4, v4, v178
	v_mul_f32_e32 v5, v5, v173
	v_mul_f32_e32 v180, v180, v179
	v_mul_f32_e32 v181, v181, v177
	v_mul_f32_e32 v4, v4, v180
	v_mul_f32_e32 v5, v5, v181
	v_cvt_pk_bf16_f32 v6, v6, v7
	v_cvt_pk_bf16_f32 v7, v8, v9
	v_cvt_pk_bf16_f32 v8, v2, v3
	v_cvt_pk_bf16_f32 v9, v4, v5
	global_store_dwordx4 v[146:147], v[6:9], off offset:256
	s_andn2_b64 vcc, exec, s[38:39]
	s_mov_b64 s[4:5], -1
	s_cbranch_vccnz .LBB0_686
	s_andn2_b64 vcc, exec, s[42:43]
	s_cbranch_vccnz .LBB0_685
	s_barrier
	s_branch .LBB0_685
	s_nop 0
	s_nop 0
	s_nop 0
	s_nop 0
	s_nop 0
	s_nop 0
	s_nop 0
	s_nop 0
	s_nop 0
	s_nop 0
	s_nop 0
	s_nop 0
	s_nop 0
	s_nop 0
	s_nop 0
	s_nop 0
	s_nop 0
	s_nop 0
	s_nop 0
	s_nop 0
	s_nop 0
	s_nop 0
	s_nop 0
	s_nop 0
	s_nop 0
	s_nop 0
	s_nop 0
	s_nop 0
	s_nop 0
	s_nop 0
	s_nop 0
